# P6 up-projection: running gated sum kept in f32 accumulators across the 3 branch units (scale by gate ratios), single bf16 store; no partial-sum round trip
# speedup vs baseline: 1.0256x; 1.0233x over previous
; #define PG8_STAGE(bufoff, gbase, voff) do { _Pragma("unroll") for (int _i = 0; _i < 2; ++_i) \
;         __builtin_amdgcn_global_load_lds((const unsigned*)((const char*)(gbase) + (voff)[_i]), (LAS unsigned*)(lds + (bufoff) + ldsw + _i * 8192), 16, 0, 0); } while (0)
; #define PG8_LDA(dst, b, h) do { _Pragma("unroll") for (int m = 0; m < 4; ++m) _Pragma("unroll") for (int k = 0; k < 2; ++k) dst[m][k] = *(const LAS bf16x8*)(lds + PG8_SA(b, h) + aoff + m * 2048 + k * 1024); } while (0)
; #define PG8_LDB(dst, b, h) do { _Pragma("unroll") for (int n = 0; n < 2; ++n) _Pragma("unroll") for (int k = 0; k < 2; ++k) dst[n][k] = *(const LAS bf16x8*)(lds + PG8_SB(b, h) + boff + n * 2048 + k * 1024); } while (0)
; #define PG8_MMA(ai, bj, At, Bt) do { __builtin_amdgcn_s_setprio(1); _Pragma("unroll") for (int m = 0; m < 4; ++m) _Pragma("unroll") for (int n = 0; n < 2; ++n) _Pragma("unroll") for (int k = 0; k < 2; ++k) \
;         acc[ai][bj][m][n] = __builtin_amdgcn_mfma_f32_16x16x32_bf16(Bt[n][k], At[m][k], acc[ai][bj][m][n], 0, 0, 0); __builtin_amdgcn_s_setprio(0); } while (0)
; #define PG8_WAIT_V(n) asm volatile("s_waitcnt vmcnt(" #n ")" ::: "memory")
; template <class Epi, class Sched>
; DI void gemm_phase(LAS unsigned char* lds, const Sched& S, const Epi& E) {
;     ...
;         const bool has_next = S.next(ui + 1, nxt);
;         const char* nA = has_next ? S.pa(nxt) : cA; const char* nB = has_next ? S.pb(nxt) : cB;
;         for (int t = 0; t < nt; t += 2) {
;             const bool last = (t == nt - 2);
;             const char* a1 = cA + (size_t)(t + 1) * kstep;
;             const char* a2 = last ? nA : cA + (size_t)(t + 2) * kstep; const char* b2 = last ? nB : cB + (size_t)(t + 2) * kstep;
;             const char* a3 = a2 + kstep; const char* b3 = b2 + kstep;
;             PG8_LDB(B0, 0, 0); PG8_LDB(B1, 0, 1); PG8_SCHED; PG8_LDA(At, 0, 0); PG8_STAGE(PG8_SA(1, 1), a1 + hstepA, voffA);
;             PG8_WAIT_V(8); PG8_WAIT_L(0); PG8_BAR; PG8_MMA(0, 0, At, B0); PG8_MMA(0, 1, At, B1); PG8_BAR; PG8_SCHED;
;     ...
; #pragma unroll
;         for (int a = 0; a < 2; ++a)
; #pragma unroll
;             for (int b = 0; b < 2; ++b)
; #pragma unroll
;                 for (int m = 0; m < 4; ++m)
; #pragma unroll
;                     for (int n = 0; n < 2; ++n) acc[a][b][m][n] = (f32x4){0.f, 0.f, 0.f, 0.f};
;         cur = nxt; cA = nA; cB = nB; ++ui;
.LBB0_1260:
	v_cndmask_b32_e64 v146, 0, 1, s[26:27]
	v_cmp_ne_u32_e64 s[4:5], 1, v146
	s_andn2_b64 vcc, exec, s[26:27]
	s_mov_b64 s[18:19], s[22:23]
	s_cbranch_vccnz .LBB0_1262
	s_cmp_eq_u32 s66, 1
	s_cselect_b32 s18, s37, 0x1600
	s_cmp_lg_u32 s66, 0
	s_mul_i32 s20, s59, 0x320000
	s_cselect_b32 s18, s18, 0
	s_mul_hi_i32 s19, s59, 0x320000
	s_add_u32 s20, s48, s20
	s_addc_u32 s19, s49, s19
	s_add_u32 s18, s20, s18
	s_addc_u32 s19, s19, 0
.LBB0_1262:
	s_lshl_b32 s20, s66, 10
	s_lshl_b32 s21, s58, 8
	s_add_i32 s20, s21, s20
	s_ashr_i32 s21, s20, 31
	s_lshl_b64 s[20:21], s[20:21], 10
	s_add_u32 s20, s3, s20
	s_addc_u32 s21, s45, s21
	s_and_b64 s[26:27], s[26:27], exec
	s_cselect_b32 s70, s21, s25
	s_cselect_b32 s71, s20, s24
	s_add_u32 s22, s22, 0x190080
	s_addc_u32 s23, s23, 0
	s_add_u32 s72, s24, 0x100
	s_addc_u32 s73, s25, 0
	s_mov_b32 s74, -2
	s_cmp_lg_u32 s67, 0
	s_cbranch_scc1 .Lup6_nozero
	v_mov_b32_e32 v2, 0
	v_mov_b32_e32 v3, v2
	v_mov_b32_e32 v4, v2
	v_mov_b32_e32 v5, v2
	v_mov_b32_e32 v6, v2
	v_mov_b32_e32 v7, v2
	v_mov_b32_e32 v8, v2
	v_mov_b32_e32 v9, v2
	v_mov_b32_e32 v10, v2
	v_mov_b32_e32 v11, v2
	v_mov_b32_e32 v12, v2
	v_mov_b32_e32 v13, v2
	v_mov_b32_e32 v18, v2
	v_mov_b32_e32 v19, v2
	v_mov_b32_e32 v20, v2
	v_mov_b32_e32 v21, v2
	v_mov_b32_e32 v26, v2
	v_mov_b32_e32 v27, v2
	v_mov_b32_e32 v28, v2
	v_mov_b32_e32 v29, v2
	v_mov_b32_e32 v34, v2
	v_mov_b32_e32 v35, v2
	v_mov_b32_e32 v36, v2
	v_mov_b32_e32 v37, v2
	v_mov_b32_e32 v42, v2
	v_mov_b32_e32 v43, v2
	v_mov_b32_e32 v44, v2
	v_mov_b32_e32 v45, v2
	v_mov_b32_e32 v50, v2
	v_mov_b32_e32 v51, v2
	v_mov_b32_e32 v52, v2
	v_mov_b32_e32 v53, v2
	v_mov_b32_e32 v14, v2
	v_mov_b32_e32 v15, v2
	v_mov_b32_e32 v16, v2
	v_mov_b32_e32 v17, v2
	v_mov_b32_e32 v22, v2
	v_mov_b32_e32 v23, v2
	v_mov_b32_e32 v24, v2
	v_mov_b32_e32 v25, v2
	v_mov_b32_e32 v30, v2
	v_mov_b32_e32 v31, v2
	v_mov_b32_e32 v32, v2
	v_mov_b32_e32 v33, v2
	v_mov_b32_e32 v38, v2
	v_mov_b32_e32 v39, v2
	v_mov_b32_e32 v40, v2
	v_mov_b32_e32 v41, v2
	v_mov_b32_e32 v46, v2
	v_mov_b32_e32 v47, v2
	v_mov_b32_e32 v48, v2
	v_mov_b32_e32 v49, v2
	v_mov_b32_e32 v54, v2
	v_mov_b32_e32 v55, v2
	v_mov_b32_e32 v56, v2
	v_mov_b32_e32 v57, v2
	v_mov_b32_e32 v58, v2
	v_mov_b32_e32 v59, v2
	v_mov_b32_e32 v60, v2
	v_mov_b32_e32 v61, v2
	v_mov_b32_e32 v62, v2
	v_mov_b32_e32 v63, v2
	v_mov_b32_e32 v64, v2
	v_mov_b32_e32 v65, v2
	v_mov_b32_e32 v66, v2
	v_mov_b32_e32 v67, v2
	v_mov_b32_e32 v68, v2
	v_mov_b32_e32 v69, v2
	v_mov_b32_e32 v70, v2
	v_mov_b32_e32 v71, v2
	v_mov_b32_e32 v72, v2
	v_mov_b32_e32 v73, v2
	v_mov_b32_e32 v74, v2
	v_mov_b32_e32 v75, v2
	v_mov_b32_e32 v76, v2
	v_mov_b32_e32 v77, v2
	v_mov_b32_e32 v82, v2
	v_mov_b32_e32 v83, v2
	v_mov_b32_e32 v84, v2
	v_mov_b32_e32 v85, v2
	v_mov_b32_e32 v90, v2
	v_mov_b32_e32 v91, v2
	v_mov_b32_e32 v92, v2
	v_mov_b32_e32 v93, v2
	v_mov_b32_e32 v98, v2
	v_mov_b32_e32 v99, v2
	v_mov_b32_e32 v100, v2
	v_mov_b32_e32 v101, v2
	v_mov_b32_e32 v110, v2
	v_mov_b32_e32 v111, v2
	v_mov_b32_e32 v112, v2
	v_mov_b32_e32 v113, v2
	v_mov_b32_e32 v114, v2
	v_mov_b32_e32 v115, v2
	v_mov_b32_e32 v116, v2
	v_mov_b32_e32 v117, v2
	v_mov_b32_e32 v78, v2
	v_mov_b32_e32 v79, v2
	v_mov_b32_e32 v80, v2
	v_mov_b32_e32 v81, v2
	v_mov_b32_e32 v86, v2
	v_mov_b32_e32 v87, v2
	v_mov_b32_e32 v88, v2
	v_mov_b32_e32 v89, v2
	v_mov_b32_e32 v94, v2
	v_mov_b32_e32 v95, v2
	v_mov_b32_e32 v96, v2
	v_mov_b32_e32 v97, v2
	v_mov_b32_e32 v102, v2
	v_mov_b32_e32 v103, v2
	v_mov_b32_e32 v104, v2
	v_mov_b32_e32 v105, v2
	v_mov_b32_e32 v106, v2
	v_mov_b32_e32 v107, v2
	v_mov_b32_e32 v108, v2
	v_mov_b32_e32 v109, v2
	v_mov_b32_e32 v118, v2
	v_mov_b32_e32 v119, v2
	v_mov_b32_e32 v120, v2
	v_mov_b32_e32 v121, v2
	v_mov_b32_e32 v122, v2
	v_mov_b32_e32 v123, v2
	v_mov_b32_e32 v124, v2
	v_mov_b32_e32 v125, v2
	v_mov_b32_e32 v126, v2
	v_mov_b32_e32 v127, v2
	v_mov_b32_e32 v128, v2
	v_mov_b32_e32 v129, v2
.Lup6_nozero:
	s_waitcnt vmcnt(0)
.LBB0_1263:
	ds_read_b128 v[130:133], v172
	ds_read_b128 v[134:137], v172 offset:1024
	ds_read_b128 v[138:141], v172 offset:2048
	ds_read_b128 v[142:145], v172 offset:3072
	ds_read_b128 v[146:149], v173
	ds_read_b128 v[150:153], v173 offset:1024
	ds_read_b128 v[166:169], v173 offset:2048
	ds_read_b128 v[176:179], v173 offset:3072
	s_add_u32 s24, s22, 0xffe70080
	s_addc_u32 s25, s23, -1
	s_cmp_eq_u32 s74, 4
	s_cselect_b32 s27, s19, s25
	s_cselect_b32 s26, s18, s24
	s_cselect_b32 s25, s70, s73
	s_cselect_b32 s24, s71, s72
	v_lshl_add_u64 v[180:181], s[22:23], 0, v[162:163]
	s_add_i32 m0, s29, 0xc000
	ds_read_b128 v[184:187], v174
	ds_read_b128 v[188:191], v174 offset:1024
	ds_read_b128 v[192:195], v174 offset:2048
	ds_read_b128 v[196:199], v174 offset:3072
	ds_read_b128 v[200:203], v174 offset:4096
	ds_read_b128 v[204:207], v174 offset:5120
	ds_read_b128 v[208:211], v174 offset:6144
	ds_read_b128 v[212:215], v174 offset:7168
	global_load_lds_dwordx4 v[180:181], off
	v_lshl_add_u64 v[180:181], s[22:23], 0, v[164:165]
	s_add_i32 m0, s29, 0xe000
	s_nop 0
	global_load_lds_dwordx4 v[180:181], off
	s_waitcnt vmcnt(8)
	s_waitcnt lgkmcnt(0)
	s_barrier
; #define PG8_STAGE(bufoff, gbase, voff) do { _Pragma("unroll") for (int _i = 0; _i < 2; ++_i) \
;         __builtin_amdgcn_global_load_lds((const unsigned*)((const char*)(gbase) + (voff)[_i]), (LAS unsigned*)(lds + (bufoff) + ldsw + _i * 8192), 16, 0, 0); } while (0)
; #define PG8_LDA(dst, b, h) do { _Pragma("unroll") for (int m = 0; m < 4; ++m) _Pragma("unroll") for (int k = 0; k < 2; ++k) dst[m][k] = *(const LAS bf16x8*)(lds + PG8_SA(b, h) + aoff + m * 2048 + k * 1024); } while (0)
; #define PG8_MMA(ai, bj, At, Bt) do { __builtin_amdgcn_s_setprio(1); _Pragma("unroll") for (int m = 0; m < 4; ++m) _Pragma("unroll") for (int n = 0; n < 2; ++n) _Pragma("unroll") for (int k = 0; k < 2; ++k) \
;         acc[ai][bj][m][n] = __builtin_amdgcn_mfma_f32_16x16x32_bf16(Bt[n][k], At[m][k], acc[ai][bj][m][n], 0, 0, 0); __builtin_amdgcn_s_setprio(0); } while (0)
; #define PG8_WAIT_V(n) asm volatile("s_waitcnt vmcnt(" #n ")" ::: "memory")
; #define PG8_WAIT_L(n) asm volatile("s_waitcnt lgkmcnt(" #n ")" ::: "memory")
; #define PG8_BAR __builtin_amdgcn_s_barrier()
; #define PG8_SCHED __builtin_amdgcn_sched_barrier(0)
; template <class Epi, class Sched>
; DI void gemm_phase(LAS unsigned char* lds, const Sched& S, const Epi& E) {
;     ...
;             PG8_WAIT_V(8); PG8_WAIT_L(0); PG8_BAR; PG8_MMA(0, 0, At, B0); PG8_MMA(0, 1, At, B1); PG8_BAR; PG8_SCHED;
;             PG8_LDA(At, 0, 1); PG8_STAGE(PG8_SB(0, 0), b2, voffB); PG8_STAGE(PG8_SB(0, 1), b2 + hstepB, voffB); PG8_STAGE(PG8_SA(0, 0), a2, voffA);
;             PG8_WAIT_V(8); PG8_WAIT_L(0); PG8_BAR; PG8_MMA(1, 0, At, B0); PG8_MMA(1, 1, At, B1); PG8_BAR; PG8_SCHED;
	s_setprio 1
	s_waitcnt lgkmcnt(0)
	v_mfma_f32_16x16x32_bf16 v[126:129], v[130:133], v[184:187], v[126:129]
	v_mfma_f32_16x16x32_bf16 v[122:125], v[138:141], v[184:187], v[122:125]
	v_mfma_f32_16x16x32_bf16 v[118:121], v[130:133], v[192:195], v[118:121]
	v_mfma_f32_16x16x32_bf16 v[106:109], v[138:141], v[192:195], v[106:109]
	v_mfma_f32_16x16x32_bf16 v[102:105], v[130:133], v[200:203], v[102:105]
	v_mfma_f32_16x16x32_bf16 v[94:97], v[138:141], v[200:203], v[94:97]
	v_mfma_f32_16x16x32_bf16 v[86:89], v[130:133], v[208:211], v[86:89]
	v_mfma_f32_16x16x32_bf16 v[78:81], v[138:141], v[208:211], v[78:81]
	v_mfma_f32_16x16x32_bf16 v[126:129], v[134:137], v[188:191], v[126:129]
	v_mfma_f32_16x16x32_bf16 v[122:125], v[142:145], v[188:191], v[122:125]
	v_mfma_f32_16x16x32_bf16 v[118:121], v[134:137], v[196:199], v[118:121]
	v_mfma_f32_16x16x32_bf16 v[106:109], v[142:145], v[196:199], v[106:109]
	v_mfma_f32_16x16x32_bf16 v[102:105], v[134:137], v[204:207], v[102:105]
	v_mfma_f32_16x16x32_bf16 v[94:97], v[142:145], v[204:207], v[94:97]
	v_mfma_f32_16x16x32_bf16 v[86:89], v[134:137], v[212:215], v[86:89]
	v_mfma_f32_16x16x32_bf16 v[78:81], v[142:145], v[212:215], v[78:81]
	s_setprio 0
	s_setprio 1
	v_mfma_f32_16x16x32_bf16 v[114:117], v[146:149], v[184:187], v[114:117]
	v_mfma_f32_16x16x32_bf16 v[110:113], v[166:169], v[184:187], v[110:113]
	v_mfma_f32_16x16x32_bf16 v[98:101], v[146:149], v[192:195], v[98:101]
	v_mfma_f32_16x16x32_bf16 v[90:93], v[166:169], v[192:195], v[90:93]
	v_mfma_f32_16x16x32_bf16 v[82:85], v[146:149], v[200:203], v[82:85]
	v_mfma_f32_16x16x32_bf16 v[74:77], v[166:169], v[200:203], v[74:77]
	v_mfma_f32_16x16x32_bf16 v[70:73], v[146:149], v[208:211], v[70:73]
	v_mfma_f32_16x16x32_bf16 v[66:69], v[166:169], v[208:211], v[66:69]
	v_mfma_f32_16x16x32_bf16 v[114:117], v[150:153], v[188:191], v[114:117]
	v_mfma_f32_16x16x32_bf16 v[110:113], v[176:179], v[188:191], v[110:113]
	v_mfma_f32_16x16x32_bf16 v[98:101], v[150:153], v[196:199], v[98:101]
	v_mfma_f32_16x16x32_bf16 v[90:93], v[176:179], v[196:199], v[90:93]
	v_mfma_f32_16x16x32_bf16 v[82:85], v[150:153], v[204:207], v[82:85]
	v_mfma_f32_16x16x32_bf16 v[74:77], v[176:179], v[204:207], v[74:77]
	v_mfma_f32_16x16x32_bf16 v[70:73], v[150:153], v[212:215], v[70:73]
	v_mfma_f32_16x16x32_bf16 v[66:69], v[176:179], v[212:215], v[66:69]
	s_setprio 0
	s_barrier
	s_add_i32 s75, s38, s28
	v_lshl_add_u64 v[180:181], s[24:25], 0, v[156:157]
	s_mov_b32 m0, s75
	ds_read_b128 v[184:187], v174 offset:16384
	ds_read_b128 v[188:191], v174 offset:17408
	ds_read_b128 v[192:195], v174 offset:18432
	ds_read_b128 v[196:199], v174 offset:19456
	ds_read_b128 v[200:203], v174 offset:20480
	ds_read_b128 v[204:207], v174 offset:21504
	ds_read_b128 v[208:211], v174 offset:22528
	ds_read_b128 v[212:215], v174 offset:23552
	global_load_lds_dwordx4 v[180:181], off
	s_add_i32 m0, s75, 0x2000
	s_add_u32 s76, s24, 0x20000
	v_lshl_add_u64 v[216:217], s[24:25], 0, v[160:161]
	s_addc_u32 s77, s25, 0
	s_add_i32 s75, s39, s28
	global_load_lds_dwordx4 v[216:217], off
	v_lshl_add_u64 v[218:219], s[76:77], 0, v[156:157]
	s_mov_b32 m0, s75
	v_lshl_add_u64 v[220:221], s[26:27], 0, v[158:159]
	global_load_lds_dwordx4 v[218:219], off
	v_lshl_add_u64 v[218:219], s[76:77], 0, v[160:161]
	s_add_i32 m0, s75, 0x2000
	s_nop 0
	global_load_lds_dwordx4 v[218:219], off
	v_lshl_add_u64 v[218:219], s[26:27], 0, v[154:155]
	s_mov_b32 m0, s29
	s_nop 0
	global_load_lds_dwordx4 v[218:219], off
	s_mov_b32 m0, s30
	s_nop 0
	global_load_lds_dwordx4 v[220:221], off
	s_waitcnt vmcnt(8)
	s_waitcnt lgkmcnt(0)
	s_barrier
	s_setprio 1
	s_waitcnt lgkmcnt(0)
	v_mfma_f32_16x16x32_bf16 v[62:65], v[130:133], v[184:187], v[62:65]
	v_mfma_f32_16x16x32_bf16 v[58:61], v[138:141], v[184:187], v[58:61]
	v_mfma_f32_16x16x32_bf16 v[54:57], v[130:133], v[192:195], v[54:57]
	v_mfma_f32_16x16x32_bf16 v[46:49], v[138:141], v[192:195], v[46:49]
	v_mfma_f32_16x16x32_bf16 v[38:41], v[130:133], v[200:203], v[38:41]
	v_mfma_f32_16x16x32_bf16 v[30:33], v[138:141], v[200:203], v[30:33]
	v_mfma_f32_16x16x32_bf16 v[22:25], v[130:133], v[208:211], v[22:25]
	v_mfma_f32_16x16x32_bf16 v[14:17], v[138:141], v[208:211], v[14:17]
	v_mfma_f32_16x16x32_bf16 v[62:65], v[134:137], v[188:191], v[62:65]
	v_mfma_f32_16x16x32_bf16 v[58:61], v[142:145], v[188:191], v[58:61]
	v_mfma_f32_16x16x32_bf16 v[54:57], v[134:137], v[196:199], v[54:57]
	v_mfma_f32_16x16x32_bf16 v[46:49], v[142:145], v[196:199], v[46:49]
	v_mfma_f32_16x16x32_bf16 v[38:41], v[134:137], v[204:207], v[38:41]
	v_mfma_f32_16x16x32_bf16 v[30:33], v[142:145], v[204:207], v[30:33]
	v_mfma_f32_16x16x32_bf16 v[22:25], v[134:137], v[212:215], v[22:25]
	v_mfma_f32_16x16x32_bf16 v[14:17], v[142:145], v[212:215], v[14:17]
	s_setprio 0
	s_setprio 1
	v_mfma_f32_16x16x32_bf16 v[50:53], v[146:149], v[184:187], v[50:53]
	v_mfma_f32_16x16x32_bf16 v[42:45], v[166:169], v[184:187], v[42:45]
	v_mfma_f32_16x16x32_bf16 v[34:37], v[146:149], v[192:195], v[34:37]
	v_mfma_f32_16x16x32_bf16 v[26:29], v[166:169], v[192:195], v[26:29]
	v_mfma_f32_16x16x32_bf16 v[18:21], v[146:149], v[200:203], v[18:21]
	v_mfma_f32_16x16x32_bf16 v[10:13], v[166:169], v[200:203], v[10:13]
	v_mfma_f32_16x16x32_bf16 v[6:9], v[146:149], v[208:211], v[6:9]
	v_mfma_f32_16x16x32_bf16 v[2:5], v[166:169], v[208:211], v[2:5]
	v_mfma_f32_16x16x32_bf16 v[50:53], v[150:153], v[188:191], v[50:53]
	v_mfma_f32_16x16x32_bf16 v[42:45], v[176:179], v[188:191], v[42:45]
	v_mfma_f32_16x16x32_bf16 v[34:37], v[150:153], v[196:199], v[34:37]
	v_mfma_f32_16x16x32_bf16 v[26:29], v[176:179], v[196:199], v[26:29]
	v_mfma_f32_16x16x32_bf16 v[18:21], v[150:153], v[204:207], v[18:21]
	v_mfma_f32_16x16x32_bf16 v[10:13], v[176:179], v[204:207], v[10:13]
	v_mfma_f32_16x16x32_bf16 v[6:9], v[150:153], v[212:215], v[6:9]
	v_mfma_f32_16x16x32_bf16 v[2:5], v[176:179], v[212:215], v[2:5]
	s_setprio 0
	s_barrier
; #define PG8_STAGE(bufoff, gbase, voff) do { _Pragma("unroll") for (int _i = 0; _i < 2; ++_i) \
;         __builtin_amdgcn_global_load_lds((const unsigned*)((const char*)(gbase) + (voff)[_i]), (LAS unsigned*)(lds + (bufoff) + ldsw + _i * 8192), 16, 0, 0); } while (0)
; #define PG8_LDA(dst, b, h) do { _Pragma("unroll") for (int m = 0; m < 4; ++m) _Pragma("unroll") for (int k = 0; k < 2; ++k) dst[m][k] = *(const LAS bf16x8*)(lds + PG8_SA(b, h) + aoff + m * 2048 + k * 1024); } while (0)
; #define PG8_LDB(dst, b, h) do { _Pragma("unroll") for (int n = 0; n < 2; ++n) _Pragma("unroll") for (int k = 0; k < 2; ++k) dst[n][k] = *(const LAS bf16x8*)(lds + PG8_SB(b, h) + boff + n * 2048 + k * 1024); } while (0)
; #define PG8_MMA(ai, bj, At, Bt) do { __builtin_amdgcn_s_setprio(1); _Pragma("unroll") for (int m = 0; m < 4; ++m) _Pragma("unroll") for (int n = 0; n < 2; ++n) _Pragma("unroll") for (int k = 0; k < 2; ++k) \
;         acc[ai][bj][m][n] = __builtin_amdgcn_mfma_f32_16x16x32_bf16(Bt[n][k], At[m][k], acc[ai][bj][m][n], 0, 0, 0); __builtin_amdgcn_s_setprio(0); } while (0)
; #define PG8_WAIT_V(n) asm volatile("s_waitcnt vmcnt(" #n ")" ::: "memory")
; #define PG8_WAIT_L(n) asm volatile("s_waitcnt lgkmcnt(" #n ")" ::: "memory")
; #define PG8_BAR __builtin_amdgcn_s_barrier()
; #define PG8_SCHED __builtin_amdgcn_sched_barrier(0)
; template <class Epi, class Sched>
; DI void gemm_phase(LAS unsigned char* lds, const Sched& S, const Epi& E) {
;     ...
;             PG8_LDB(B0, 1, 0); PG8_LDB(B1, 1, 1); PG8_SCHED; PG8_LDA(At, 1, 0); PG8_STAGE(PG8_SA(0, 1), a2 + hstepA, voffA);
;             PG8_WAIT_V(8); PG8_WAIT_L(0); PG8_BAR; PG8_MMA(0, 0, At, B0); PG8_MMA(0, 1, At, B1); PG8_BAR; PG8_SCHED;
;             PG8_LDA(At, 1, 1); PG8_STAGE(PG8_SB(1, 0), b3, voffB); PG8_STAGE(PG8_SB(1, 1), b3 + hstepB, voffB); PG8_STAGE(PG8_SA(1, 0), a3, voffA);
	s_add_i32 s75, 0, 0x18000
	s_add_i32 s76, 0, 0x1c000
	v_add_u32_e32 v142, s75, v171
	v_add_u32_e32 v175, s76, v171
	ds_read_b128 v[130:133], v142
	ds_read_b128 v[134:137], v142 offset:1024
	ds_read_b128 v[138:141], v142 offset:2048
	ds_read_b128 v[142:145], v142 offset:3072
	ds_read_b128 v[146:149], v175
	ds_read_b128 v[150:153], v175 offset:1024
	ds_read_b128 v[166:169], v175 offset:2048
	ds_read_b128 v[176:179], v175 offset:3072
	s_add_u32 s26, s26, 0x190000
	s_addc_u32 s27, s27, 0
	s_mov_b32 m0, s31
	v_lshl_add_u64 v[222:223], s[26:27], 0, v[154:155]
	ds_read_b128 v[184:187], v174 offset:32768
	ds_read_b128 v[188:191], v174 offset:33792
	ds_read_b128 v[192:195], v174 offset:34816
	ds_read_b128 v[196:199], v174 offset:35840
	ds_read_b128 v[200:203], v174 offset:36864
	ds_read_b128 v[204:207], v174 offset:37888
	ds_read_b128 v[208:211], v174 offset:38912
	ds_read_b128 v[212:215], v174 offset:39936
	global_load_lds_dwordx4 v[222:223], off
	v_lshl_add_u64 v[222:223], s[26:27], 0, v[158:159]
	s_mov_b32 m0, s33
	s_nop 0
	global_load_lds_dwordx4 v[222:223], off
	s_waitcnt vmcnt(8)
	s_waitcnt lgkmcnt(0)
	s_barrier
	s_setprio 1
	s_waitcnt lgkmcnt(0)
	v_mfma_f32_16x16x32_bf16 v[126:129], v[130:133], v[184:187], v[126:129]
	v_mfma_f32_16x16x32_bf16 v[122:125], v[138:141], v[184:187], v[122:125]
	v_mfma_f32_16x16x32_bf16 v[118:121], v[130:133], v[192:195], v[118:121]
	v_mfma_f32_16x16x32_bf16 v[106:109], v[138:141], v[192:195], v[106:109]
	v_mfma_f32_16x16x32_bf16 v[102:105], v[130:133], v[200:203], v[102:105]
	v_mfma_f32_16x16x32_bf16 v[94:97], v[138:141], v[200:203], v[94:97]
	v_mfma_f32_16x16x32_bf16 v[86:89], v[130:133], v[208:211], v[86:89]
	v_mfma_f32_16x16x32_bf16 v[78:81], v[138:141], v[208:211], v[78:81]
	v_mfma_f32_16x16x32_bf16 v[126:129], v[134:137], v[188:191], v[126:129]
	v_mfma_f32_16x16x32_bf16 v[122:125], v[142:145], v[188:191], v[122:125]
	v_mfma_f32_16x16x32_bf16 v[118:121], v[134:137], v[196:199], v[118:121]
	v_mfma_f32_16x16x32_bf16 v[106:109], v[142:145], v[196:199], v[106:109]
	v_mfma_f32_16x16x32_bf16 v[102:105], v[134:137], v[204:207], v[102:105]
	v_mfma_f32_16x16x32_bf16 v[94:97], v[142:145], v[204:207], v[94:97]
	v_mfma_f32_16x16x32_bf16 v[86:89], v[134:137], v[212:215], v[86:89]
	v_mfma_f32_16x16x32_bf16 v[78:81], v[142:145], v[212:215], v[78:81]
	s_setprio 0
	s_setprio 1
	v_mfma_f32_16x16x32_bf16 v[114:117], v[146:149], v[184:187], v[114:117]
	v_mfma_f32_16x16x32_bf16 v[110:113], v[166:169], v[184:187], v[110:113]
	v_mfma_f32_16x16x32_bf16 v[98:101], v[146:149], v[192:195], v[98:101]
	v_mfma_f32_16x16x32_bf16 v[90:93], v[166:169], v[192:195], v[90:93]
	v_mfma_f32_16x16x32_bf16 v[82:85], v[146:149], v[200:203], v[82:85]
	v_mfma_f32_16x16x32_bf16 v[74:77], v[166:169], v[200:203], v[74:77]
	v_mfma_f32_16x16x32_bf16 v[70:73], v[146:149], v[208:211], v[70:73]
	v_mfma_f32_16x16x32_bf16 v[66:69], v[166:169], v[208:211], v[66:69]
	v_mfma_f32_16x16x32_bf16 v[114:117], v[150:153], v[188:191], v[114:117]
	v_mfma_f32_16x16x32_bf16 v[110:113], v[176:179], v[188:191], v[110:113]
	v_mfma_f32_16x16x32_bf16 v[98:101], v[150:153], v[196:199], v[98:101]
	v_mfma_f32_16x16x32_bf16 v[90:93], v[176:179], v[196:199], v[90:93]
	v_mfma_f32_16x16x32_bf16 v[82:85], v[150:153], v[204:207], v[82:85]
	v_mfma_f32_16x16x32_bf16 v[74:77], v[176:179], v[204:207], v[74:77]
	v_mfma_f32_16x16x32_bf16 v[70:73], v[150:153], v[212:215], v[70:73]
	v_mfma_f32_16x16x32_bf16 v[66:69], v[176:179], v[212:215], v[66:69]
	s_setprio 0
	s_barrier
	s_add_i32 s26, s75, s28
	v_lshl_add_u64 v[180:181], v[180:181], 0, s[12:13]
	s_mov_b32 m0, s26
	ds_read_b128 v[184:187], v174 offset:49152
	ds_read_b128 v[188:191], v174 offset:50176
	ds_read_b128 v[192:195], v174 offset:51200
	ds_read_b128 v[196:199], v174 offset:52224
	ds_read_b128 v[200:203], v174 offset:53248
	ds_read_b128 v[204:207], v174 offset:54272
	ds_read_b128 v[208:211], v174 offset:55296
	ds_read_b128 v[212:215], v174 offset:56320
	global_load_lds_dwordx4 v[180:181], off
	s_add_i32 m0, s26, 0x2000
	s_add_u32 s24, s24, 0x20080
	v_lshl_add_u64 v[180:181], v[216:217], 0, s[12:13]
	s_addc_u32 s25, s25, 0
	s_add_i32 s26, s76, s28
	global_load_lds_dwordx4 v[180:181], off
	v_lshl_add_u64 v[180:181], s[24:25], 0, v[156:157]
	s_mov_b32 m0, s26
	s_nop 0
	global_load_lds_dwordx4 v[180:181], off
	v_lshl_add_u64 v[180:181], s[24:25], 0, v[160:161]
	s_add_i32 m0, s26, 0x2000
	s_nop 0
	global_load_lds_dwordx4 v[180:181], off
	v_lshl_add_u64 v[180:181], v[218:219], 0, s[12:13]
	s_mov_b32 m0, s35
	s_nop 0
	global_load_lds_dwordx4 v[180:181], off
	v_lshl_add_u64 v[180:181], v[220:221], 0, s[12:13]
	s_mov_b32 m0, s36
	s_nop 0
	global_load_lds_dwordx4 v[180:181], off
	s_waitcnt vmcnt(8)
	s_waitcnt lgkmcnt(0)
	s_barrier
; #define PG8_MMA(ai, bj, At, Bt) do { __builtin_amdgcn_s_setprio(1); _Pragma("unroll") for (int m = 0; m < 4; ++m) _Pragma("unroll") for (int n = 0; n < 2; ++n) _Pragma("unroll") for (int k = 0; k < 2; ++k) \
;         acc[ai][bj][m][n] = __builtin_amdgcn_mfma_f32_16x16x32_bf16(Bt[n][k], At[m][k], acc[ai][bj][m][n], 0, 0, 0); __builtin_amdgcn_s_setprio(0); } while (0)
; #define PG8_WAIT_V(n) asm volatile("s_waitcnt vmcnt(" #n ")" ::: "memory")
; #define PG8_WAIT_L(n) asm volatile("s_waitcnt lgkmcnt(" #n ")" ::: "memory")
; #define PG8_BAR __builtin_amdgcn_s_barrier()
; #define PG8_SCHED __builtin_amdgcn_sched_barrier(0)
; template <class Epi, class Sched>
; DI void gemm_phase(LAS unsigned char* lds, const Sched& S, const Epi& E) {
;     ...
;             PG8_WAIT_V(8); PG8_WAIT_L(0); PG8_BAR; PG8_MMA(1, 0, At, B0); PG8_MMA(1, 1, At, B1); PG8_BAR; PG8_SCHED;
;         }
;         if (wr == 0) PG8_BAR;
;         E(acc, cur, wr, wc, fr, fq);
;     DI void operator()(Acc& acc, const Unit& u, int wr, int wc, int fr, int fq) const {
;     ...
;         bf16_t* base = proj + (size_t)(u.pm * 256 + wr * 64 + fr) * NPJ + C_GL + u.pn * 256 + wc * 32 + fq * 8;
;         {
;             u32x4 g[2][4][2];
; #pragma unroll
;             for (int ai = 0; ai < 2; ++ai)
; #pragma unroll
;                 for (int m = 0; m < 4; ++m)
; #pragma unroll
;                     for (int bj = 0; bj < 2; ++bj) g[ai][m][bj] = *(const u32x4*)(base + (size_t)(ai * 128 + m * 16) * NPJ + u.k * 1024 + bj * 128);
	s_setprio 1
	s_waitcnt lgkmcnt(0)
	v_mfma_f32_16x16x32_bf16 v[62:65], v[130:133], v[184:187], v[62:65]
	v_mfma_f32_16x16x32_bf16 v[58:61], v[138:141], v[184:187], v[58:61]
	v_mfma_f32_16x16x32_bf16 v[54:57], v[130:133], v[192:195], v[54:57]
	v_mfma_f32_16x16x32_bf16 v[46:49], v[138:141], v[192:195], v[46:49]
	v_mfma_f32_16x16x32_bf16 v[38:41], v[130:133], v[200:203], v[38:41]
	v_mfma_f32_16x16x32_bf16 v[30:33], v[138:141], v[200:203], v[30:33]
	v_mfma_f32_16x16x32_bf16 v[22:25], v[130:133], v[208:211], v[22:25]
	v_mfma_f32_16x16x32_bf16 v[14:17], v[138:141], v[208:211], v[14:17]
	v_mfma_f32_16x16x32_bf16 v[62:65], v[134:137], v[188:191], v[62:65]
	v_mfma_f32_16x16x32_bf16 v[58:61], v[142:145], v[188:191], v[58:61]
	v_mfma_f32_16x16x32_bf16 v[54:57], v[134:137], v[196:199], v[54:57]
	v_mfma_f32_16x16x32_bf16 v[46:49], v[142:145], v[196:199], v[46:49]
	v_mfma_f32_16x16x32_bf16 v[38:41], v[134:137], v[204:207], v[38:41]
	v_mfma_f32_16x16x32_bf16 v[30:33], v[142:145], v[204:207], v[30:33]
	v_mfma_f32_16x16x32_bf16 v[22:25], v[134:137], v[212:215], v[22:25]
	v_mfma_f32_16x16x32_bf16 v[14:17], v[142:145], v[212:215], v[14:17]
	s_setprio 0
	s_setprio 1
	v_mfma_f32_16x16x32_bf16 v[50:53], v[146:149], v[184:187], v[50:53]
	v_mfma_f32_16x16x32_bf16 v[42:45], v[166:169], v[184:187], v[42:45]
	v_mfma_f32_16x16x32_bf16 v[34:37], v[146:149], v[192:195], v[34:37]
	v_mfma_f32_16x16x32_bf16 v[26:29], v[166:169], v[192:195], v[26:29]
	v_mfma_f32_16x16x32_bf16 v[18:21], v[146:149], v[200:203], v[18:21]
	v_mfma_f32_16x16x32_bf16 v[10:13], v[166:169], v[200:203], v[10:13]
	v_mfma_f32_16x16x32_bf16 v[6:9], v[146:149], v[208:211], v[6:9]
	v_mfma_f32_16x16x32_bf16 v[2:5], v[166:169], v[208:211], v[2:5]
	v_mfma_f32_16x16x32_bf16 v[50:53], v[150:153], v[188:191], v[50:53]
	v_mfma_f32_16x16x32_bf16 v[42:45], v[176:179], v[188:191], v[42:45]
	v_mfma_f32_16x16x32_bf16 v[34:37], v[150:153], v[196:199], v[34:37]
	v_mfma_f32_16x16x32_bf16 v[26:29], v[176:179], v[196:199], v[26:29]
	v_mfma_f32_16x16x32_bf16 v[18:21], v[150:153], v[204:207], v[18:21]
	v_mfma_f32_16x16x32_bf16 v[10:13], v[176:179], v[204:207], v[10:13]
	v_mfma_f32_16x16x32_bf16 v[6:9], v[150:153], v[212:215], v[6:9]
	v_mfma_f32_16x16x32_bf16 v[2:5], v[176:179], v[212:215], v[2:5]
	s_setprio 0
	s_barrier
	s_add_i32 s74, s74, 2
	s_add_u32 s22, s22, 0x100
	s_addc_u32 s23, s23, 0
	s_add_u32 s72, s72, 0x100
	s_addc_u32 s73, s73, 0
	s_cmp_gt_u32 s74, 5
	s_cbranch_scc0 .LBB0_1263
	s_and_b64 vcc, exec, s[14:15]
	s_cbranch_vccz .LBB0_1266
	s_barrier
.LBB0_1266:
	v_mov_b32_e32 v130, v1
	v_mov_b32_e32 v132, v170
	s_lshl_b32 s22, s69, 8
	s_add_i32 s22, s22, s34
	v_add_u32_e32 v133, s22, v130
	v_mov_b64_e32 v[130:131], s[48:49]
	v_mad_i64_i32 v[130:131], s[22:23], v133, s40, v[130:131]
	s_lshl_b32 s22, s68, 8
	s_ashr_i32 s23, s22, 31
	v_lshl_add_u64 v[130:131], s[22:23], 1, v[130:131]
	v_lshlrev_b32_e32 v132, 3, v132
	v_lshl_add_u64 v[130:131], v[130:131], 0, s[8:9]
	v_ashrrev_i32_e32 v133, 31, v132
	v_lshl_add_u64 v[130:131], v[132:133], 1, v[130:131]
	s_lshl_b32 s22, s67, 10
	v_lshl_add_u64 v[166:167], v[130:131], 0, s[16:17]
	s_ashr_i32 s23, s22, 31
	v_lshl_add_u64 v[130:131], s[22:23], 1, v[166:167]
	s_mov_b32 s101, 0
	s_mov_b32 s100, 0x32000
	v_lshl_add_u64 v[132:133], v[130:131], 0, s[100:101]
	s_mov_b32 s100, 0x64000
	v_lshl_add_u64 v[134:135], v[130:131], 0, s[100:101]
	s_mov_b32 s100, 0x96000
	v_lshl_add_u64 v[136:137], v[130:131], 0, s[100:101]
	s_mov_b32 s100, 0x190000
	v_lshl_add_u64 v[138:139], v[130:131], 0, s[100:101]
	s_mov_b32 s100, 0x1c2000
	v_lshl_add_u64 v[140:141], v[130:131], 0, s[100:101]
	s_mov_b32 s100, 0x1f4000
	v_lshl_add_u64 v[142:143], v[130:131], 0, s[100:101]
	s_mov_b32 s100, 0x226000
	v_lshl_add_u64 v[144:145], v[130:131], 0, s[100:101]
	s_mov_b32 s100, 0x0d800000
	s_cmp_eq_u32 s67, 2
	s_cbranch_scc1 .Lup6_final
	global_load_dwordx4 v[184:187], v[130:131], off
	global_load_dwordx4 v[188:191], v[130:131], off offset:256
	global_load_dwordx4 v[192:195], v[130:131], off offset:2048
	global_load_dwordx4 v[196:199], v[130:131], off offset:2304
	global_load_dwordx4 v[200:203], v[132:133], off
	global_load_dwordx4 v[204:207], v[132:133], off offset:256
	global_load_dwordx4 v[208:211], v[132:133], off offset:2048
	global_load_dwordx4 v[212:215], v[132:133], off offset:2304
	global_load_dwordx4 v[216:219], v[134:135], off
	global_load_dwordx4 v[220:223], v[134:135], off offset:256
	global_load_dwordx4 v[224:227], v[134:135], off offset:2048
	global_load_dwordx4 v[228:231], v[134:135], off offset:2304
	s_waitcnt vmcnt(8)
; DI float bflo(unsigned w) { return __uint_as_float(w << 16); }
; DI float bfhi(unsigned w) { return __uint_as_float(w & 0xffff0000u); }
;     DI void operator()(Acc& acc, const Unit& u, int wr, int wc, int fr, int fq) const {
;     ...
;         bf16_t* base = proj + (size_t)(u.pm * 256 + wr * 64 + fr) * NPJ + C_GL + u.pn * 256 + wc * 32 + fq * 8;
;         {
;             u32x4 g[2][4][2];
; #pragma unroll
;             for (int ai = 0; ai < 2; ++ai)
; #pragma unroll
;                 for (int m = 0; m < 4; ++m)
; #pragma unroll
;                     for (int bj = 0; bj < 2; ++bj) g[ai][m][bj] = *(const u32x4*)(base + (size_t)(ai * 128 + m * 16) * NPJ + u.k * 1024 + bj * 128);
; #pragma unroll
;             for (int ai = 0; ai < 2; ++ai)
; #pragma unroll
;                 for (int m = 0; m < 4; ++m)
; #pragma unroll
;                     for (int bj = 0; bj < 2; ++bj) { const u32x4 q = g[ai][m][bj]; f32x4& v0 = acc[ai][bj][m][0]; f32x4& v1 = acc[ai][bj][m][1];
;                         v0[0] *= bflo(q.x); v0[1] *= bfhi(q.x); v0[2] *= bflo(q.y); v0[3] *= bfhi(q.y); v1[0] *= bflo(q.z); v1[1] *= bfhi(q.z); v1[2] *= bflo(q.w); v1[3] *= bfhi(q.w); }
	v_lshlrev_b32_e32 v148, 16, v184
	v_and_b32_e32 v149, 0xffff0000, v184
	v_lshlrev_b32_e32 v150, 16, v192
	v_and_b32_e32 v151, 0xffff0000, v192
	v_lshlrev_b32_e32 v152, 16, v185
	v_and_b32_e32 v153, 0xffff0000, v185
	v_lshlrev_b32_e32 v168, 16, v193
	v_and_b32_e32 v169, 0xffff0000, v193
	v_max_f32_e32 v150, s100, v150
	v_max_f32_e32 v151, s100, v151
	v_max_f32_e32 v148, s100, v148
	v_max_f32_e32 v149, s100, v149
	v_max_f32_e32 v168, s100, v168
	v_max_f32_e32 v169, s100, v169
	v_max_f32_e32 v152, s100, v152
	v_max_f32_e32 v153, s100, v153
	v_rcp_f32_e32 v150, v150
	v_rcp_f32_e32 v151, v151
	v_rcp_f32_e32 v168, v168
	v_rcp_f32_e32 v169, v169
	s_nop 0
	v_pk_mul_f32 v[148:149], v[148:149], v[150:151]
	v_pk_mul_f32 v[152:153], v[152:153], v[168:169]
	v_pk_mul_f32 v[126:127], v[126:127], v[148:149]
	v_pk_mul_f32 v[128:129], v[128:129], v[152:153]
	v_lshlrev_b32_e32 v176, 16, v186
	v_and_b32_e32 v177, 0xffff0000, v186
	v_lshlrev_b32_e32 v178, 16, v194
	v_and_b32_e32 v179, 0xffff0000, v194
	v_lshlrev_b32_e32 v180, 16, v187
	v_and_b32_e32 v181, 0xffff0000, v187
	v_lshlrev_b32_e32 v244, 16, v195
	v_and_b32_e32 v245, 0xffff0000, v195
	v_max_f32_e32 v178, s100, v178
	v_max_f32_e32 v179, s100, v179
	v_max_f32_e32 v176, s100, v176
	v_max_f32_e32 v177, s100, v177
	v_max_f32_e32 v244, s100, v244
	v_max_f32_e32 v245, s100, v245
	v_max_f32_e32 v180, s100, v180
	v_max_f32_e32 v181, s100, v181
	v_rcp_f32_e32 v178, v178
	v_rcp_f32_e32 v179, v179
	v_rcp_f32_e32 v244, v244
	v_rcp_f32_e32 v245, v245
	s_nop 0
	v_pk_mul_f32 v[176:177], v[176:177], v[178:179]
	v_pk_mul_f32 v[180:181], v[180:181], v[244:245]
	v_pk_mul_f32 v[122:123], v[122:123], v[176:177]
	v_pk_mul_f32 v[124:125], v[124:125], v[180:181]
	v_lshlrev_b32_e32 v176, 16, v188
	v_and_b32_e32 v177, 0xffff0000, v188
	v_lshlrev_b32_e32 v178, 16, v196
	v_and_b32_e32 v179, 0xffff0000, v196
	v_lshlrev_b32_e32 v180, 16, v189
	v_and_b32_e32 v181, 0xffff0000, v189
	v_lshlrev_b32_e32 v244, 16, v197
	v_and_b32_e32 v245, 0xffff0000, v197
	v_max_f32_e32 v178, s100, v178
	v_max_f32_e32 v179, s100, v179
	v_max_f32_e32 v176, s100, v176
	v_max_f32_e32 v177, s100, v177
	v_max_f32_e32 v244, s100, v244
	v_max_f32_e32 v245, s100, v245
	v_max_f32_e32 v180, s100, v180
	v_max_f32_e32 v181, s100, v181
	v_rcp_f32_e32 v178, v178
	v_rcp_f32_e32 v179, v179
	v_rcp_f32_e32 v244, v244
	v_rcp_f32_e32 v245, v245
	s_nop 0
	v_pk_mul_f32 v[176:177], v[176:177], v[178:179]
	v_pk_mul_f32 v[180:181], v[180:181], v[244:245]
	v_pk_mul_f32 v[114:115], v[114:115], v[176:177]
	v_pk_mul_f32 v[116:117], v[116:117], v[180:181]
	v_lshlrev_b32_e32 v148, 16, v190
	v_and_b32_e32 v149, 0xffff0000, v190
	v_lshlrev_b32_e32 v150, 16, v198
	v_and_b32_e32 v151, 0xffff0000, v198
	v_lshlrev_b32_e32 v152, 16, v191
	v_and_b32_e32 v153, 0xffff0000, v191
	v_lshlrev_b32_e32 v168, 16, v199
	v_and_b32_e32 v169, 0xffff0000, v199
	v_max_f32_e32 v150, s100, v150
	v_max_f32_e32 v151, s100, v151
	v_max_f32_e32 v148, s100, v148
	v_max_f32_e32 v149, s100, v149
	v_max_f32_e32 v168, s100, v168
	v_max_f32_e32 v169, s100, v169
	v_max_f32_e32 v152, s100, v152
	v_max_f32_e32 v153, s100, v153
	v_rcp_f32_e32 v150, v150
	v_rcp_f32_e32 v151, v151
	v_rcp_f32_e32 v168, v168
	v_rcp_f32_e32 v169, v169
	s_nop 0
	v_pk_mul_f32 v[148:149], v[148:149], v[150:151]
	v_pk_mul_f32 v[152:153], v[152:153], v[168:169]
	v_pk_mul_f32 v[110:111], v[110:111], v[148:149]
	v_pk_mul_f32 v[112:113], v[112:113], v[152:153]
	global_load_dwordx4 v[184:187], v[136:137], off
	global_load_dwordx4 v[188:191], v[136:137], off offset:256
	global_load_dwordx4 v[192:195], v[136:137], off offset:2048
	global_load_dwordx4 v[196:199], v[136:137], off offset:2304
	s_waitcnt vmcnt(8)
	v_lshlrev_b32_e32 v148, 16, v200
	v_and_b32_e32 v149, 0xffff0000, v200
	v_lshlrev_b32_e32 v150, 16, v208
	v_and_b32_e32 v151, 0xffff0000, v208
	v_lshlrev_b32_e32 v152, 16, v201
	v_and_b32_e32 v153, 0xffff0000, v201
	v_lshlrev_b32_e32 v168, 16, v209
	v_and_b32_e32 v169, 0xffff0000, v209
	v_max_f32_e32 v150, s100, v150
	v_max_f32_e32 v151, s100, v151
	v_max_f32_e32 v148, s100, v148
	v_max_f32_e32 v149, s100, v149
	v_max_f32_e32 v168, s100, v168
	v_max_f32_e32 v169, s100, v169
	v_max_f32_e32 v152, s100, v152
	v_max_f32_e32 v153, s100, v153
	v_rcp_f32_e32 v150, v150
	v_rcp_f32_e32 v151, v151
	v_rcp_f32_e32 v168, v168
	v_rcp_f32_e32 v169, v169
	s_nop 0
	v_pk_mul_f32 v[148:149], v[148:149], v[150:151]
	v_pk_mul_f32 v[152:153], v[152:153], v[168:169]
	v_pk_mul_f32 v[118:119], v[118:119], v[148:149]
	v_pk_mul_f32 v[120:121], v[120:121], v[152:153]
	v_lshlrev_b32_e32 v176, 16, v202
	v_and_b32_e32 v177, 0xffff0000, v202
	v_lshlrev_b32_e32 v178, 16, v210
	v_and_b32_e32 v179, 0xffff0000, v210
	v_lshlrev_b32_e32 v180, 16, v203
	v_and_b32_e32 v181, 0xffff0000, v203
	v_lshlrev_b32_e32 v244, 16, v211
	v_and_b32_e32 v245, 0xffff0000, v211
	v_max_f32_e32 v178, s100, v178
	v_max_f32_e32 v179, s100, v179
	v_max_f32_e32 v176, s100, v176
	v_max_f32_e32 v177, s100, v177
	v_max_f32_e32 v244, s100, v244
	v_max_f32_e32 v245, s100, v245
	v_max_f32_e32 v180, s100, v180
	v_max_f32_e32 v181, s100, v181
	v_rcp_f32_e32 v178, v178
	v_rcp_f32_e32 v179, v179
	v_rcp_f32_e32 v244, v244
	v_rcp_f32_e32 v245, v245
	s_nop 0
	v_pk_mul_f32 v[176:177], v[176:177], v[178:179]
	v_pk_mul_f32 v[180:181], v[180:181], v[244:245]
	v_pk_mul_f32 v[106:107], v[106:107], v[176:177]
	v_pk_mul_f32 v[108:109], v[108:109], v[180:181]
	v_lshlrev_b32_e32 v176, 16, v204
	v_and_b32_e32 v177, 0xffff0000, v204
	v_lshlrev_b32_e32 v178, 16, v212
	v_and_b32_e32 v179, 0xffff0000, v212
	v_lshlrev_b32_e32 v180, 16, v205
	v_and_b32_e32 v181, 0xffff0000, v205
	v_lshlrev_b32_e32 v244, 16, v213
	v_and_b32_e32 v245, 0xffff0000, v213
; DI float bflo(unsigned w) { return __uint_as_float(w << 16); }
; DI float bfhi(unsigned w) { return __uint_as_float(w & 0xffff0000u); }
;     DI void operator()(Acc& acc, const Unit& u, int wr, int wc, int fr, int fq) const {
;     ...
;         bf16_t* base = proj + (size_t)(u.pm * 256 + wr * 64 + fr) * NPJ + C_GL + u.pn * 256 + wc * 32 + fq * 8;
;         {
;             u32x4 g[2][4][2];
; #pragma unroll
;             for (int ai = 0; ai < 2; ++ai)
; #pragma unroll
;                 for (int m = 0; m < 4; ++m)
; #pragma unroll
;                     for (int bj = 0; bj < 2; ++bj) g[ai][m][bj] = *(const u32x4*)(base + (size_t)(ai * 128 + m * 16) * NPJ + u.k * 1024 + bj * 128);
; #pragma unroll
;             for (int ai = 0; ai < 2; ++ai)
; #pragma unroll
;                 for (int m = 0; m < 4; ++m)
; #pragma unroll
;                     for (int bj = 0; bj < 2; ++bj) { const u32x4 q = g[ai][m][bj]; f32x4& v0 = acc[ai][bj][m][0]; f32x4& v1 = acc[ai][bj][m][1];
;                         v0[0] *= bflo(q.x); v0[1] *= bfhi(q.x); v0[2] *= bflo(q.y); v0[3] *= bfhi(q.y); v1[0] *= bflo(q.z); v1[1] *= bfhi(q.z); v1[2] *= bflo(q.w); v1[3] *= bfhi(q.w); }
	v_max_f32_e32 v178, s100, v178
	v_max_f32_e32 v179, s100, v179
	v_max_f32_e32 v176, s100, v176
	v_max_f32_e32 v177, s100, v177
	v_max_f32_e32 v244, s100, v244
	v_max_f32_e32 v245, s100, v245
	v_max_f32_e32 v180, s100, v180
	v_max_f32_e32 v181, s100, v181
	v_rcp_f32_e32 v178, v178
	v_rcp_f32_e32 v179, v179
	v_rcp_f32_e32 v244, v244
	v_rcp_f32_e32 v245, v245
	s_nop 0
	v_pk_mul_f32 v[176:177], v[176:177], v[178:179]
	v_pk_mul_f32 v[180:181], v[180:181], v[244:245]
	v_pk_mul_f32 v[98:99], v[98:99], v[176:177]
	v_pk_mul_f32 v[100:101], v[100:101], v[180:181]
	v_lshlrev_b32_e32 v148, 16, v206
	v_and_b32_e32 v149, 0xffff0000, v206
	v_lshlrev_b32_e32 v150, 16, v214
	v_and_b32_e32 v151, 0xffff0000, v214
	v_lshlrev_b32_e32 v152, 16, v207
	v_and_b32_e32 v153, 0xffff0000, v207
	v_lshlrev_b32_e32 v168, 16, v215
	v_and_b32_e32 v169, 0xffff0000, v215
	v_max_f32_e32 v150, s100, v150
	v_max_f32_e32 v151, s100, v151
	v_max_f32_e32 v148, s100, v148
	v_max_f32_e32 v149, s100, v149
	v_max_f32_e32 v168, s100, v168
	v_max_f32_e32 v169, s100, v169
	v_max_f32_e32 v152, s100, v152
	v_max_f32_e32 v153, s100, v153
	v_rcp_f32_e32 v150, v150
	v_rcp_f32_e32 v151, v151
	v_rcp_f32_e32 v168, v168
	v_rcp_f32_e32 v169, v169
	s_nop 0
	v_pk_mul_f32 v[148:149], v[148:149], v[150:151]
	v_pk_mul_f32 v[152:153], v[152:153], v[168:169]
	v_pk_mul_f32 v[90:91], v[90:91], v[148:149]
	v_pk_mul_f32 v[92:93], v[92:93], v[152:153]
	global_load_dwordx4 v[200:203], v[138:139], off
	global_load_dwordx4 v[204:207], v[138:139], off offset:256
	global_load_dwordx4 v[208:211], v[138:139], off offset:2048
	global_load_dwordx4 v[212:215], v[138:139], off offset:2304
	s_waitcnt vmcnt(8)
	v_lshlrev_b32_e32 v148, 16, v216
	v_and_b32_e32 v149, 0xffff0000, v216
	v_lshlrev_b32_e32 v150, 16, v224
	v_and_b32_e32 v151, 0xffff0000, v224
	v_lshlrev_b32_e32 v152, 16, v217
	v_and_b32_e32 v153, 0xffff0000, v217
	v_lshlrev_b32_e32 v168, 16, v225
	v_and_b32_e32 v169, 0xffff0000, v225
	v_max_f32_e32 v150, s100, v150
	v_max_f32_e32 v151, s100, v151
	v_max_f32_e32 v148, s100, v148
	v_max_f32_e32 v149, s100, v149
	v_max_f32_e32 v168, s100, v168
	v_max_f32_e32 v169, s100, v169
	v_max_f32_e32 v152, s100, v152
	v_max_f32_e32 v153, s100, v153
	v_rcp_f32_e32 v150, v150
	v_rcp_f32_e32 v151, v151
	v_rcp_f32_e32 v168, v168
	v_rcp_f32_e32 v169, v169
	s_nop 0
	v_pk_mul_f32 v[148:149], v[148:149], v[150:151]
	v_pk_mul_f32 v[152:153], v[152:153], v[168:169]
	v_pk_mul_f32 v[102:103], v[102:103], v[148:149]
	v_pk_mul_f32 v[104:105], v[104:105], v[152:153]
	v_lshlrev_b32_e32 v176, 16, v218
	v_and_b32_e32 v177, 0xffff0000, v218
	v_lshlrev_b32_e32 v178, 16, v226
	v_and_b32_e32 v179, 0xffff0000, v226
	v_lshlrev_b32_e32 v180, 16, v219
	v_and_b32_e32 v181, 0xffff0000, v219
	v_lshlrev_b32_e32 v244, 16, v227
	v_and_b32_e32 v245, 0xffff0000, v227
	v_max_f32_e32 v178, s100, v178
	v_max_f32_e32 v179, s100, v179
	v_max_f32_e32 v176, s100, v176
	v_max_f32_e32 v177, s100, v177
	v_max_f32_e32 v244, s100, v244
	v_max_f32_e32 v245, s100, v245
	v_max_f32_e32 v180, s100, v180
	v_max_f32_e32 v181, s100, v181
	v_rcp_f32_e32 v178, v178
	v_rcp_f32_e32 v179, v179
	v_rcp_f32_e32 v244, v244
	v_rcp_f32_e32 v245, v245
	s_nop 0
	v_pk_mul_f32 v[176:177], v[176:177], v[178:179]
	v_pk_mul_f32 v[180:181], v[180:181], v[244:245]
	v_pk_mul_f32 v[94:95], v[94:95], v[176:177]
	v_pk_mul_f32 v[96:97], v[96:97], v[180:181]
	v_lshlrev_b32_e32 v176, 16, v220
	v_and_b32_e32 v177, 0xffff0000, v220
	v_lshlrev_b32_e32 v178, 16, v228
	v_and_b32_e32 v179, 0xffff0000, v228
	v_lshlrev_b32_e32 v180, 16, v221
	v_and_b32_e32 v181, 0xffff0000, v221
	v_lshlrev_b32_e32 v244, 16, v229
	v_and_b32_e32 v245, 0xffff0000, v229
	v_max_f32_e32 v178, s100, v178
	v_max_f32_e32 v179, s100, v179
	v_max_f32_e32 v176, s100, v176
	v_max_f32_e32 v177, s100, v177
	v_max_f32_e32 v244, s100, v244
	v_max_f32_e32 v245, s100, v245
	v_max_f32_e32 v180, s100, v180
	v_max_f32_e32 v181, s100, v181
	v_rcp_f32_e32 v178, v178
	v_rcp_f32_e32 v179, v179
	v_rcp_f32_e32 v244, v244
	v_rcp_f32_e32 v245, v245
	s_nop 0
	v_pk_mul_f32 v[176:177], v[176:177], v[178:179]
	v_pk_mul_f32 v[180:181], v[180:181], v[244:245]
	v_pk_mul_f32 v[82:83], v[82:83], v[176:177]
	v_pk_mul_f32 v[84:85], v[84:85], v[180:181]
	v_lshlrev_b32_e32 v148, 16, v222
	v_and_b32_e32 v149, 0xffff0000, v222
	v_lshlrev_b32_e32 v150, 16, v230
	v_and_b32_e32 v151, 0xffff0000, v230
	v_lshlrev_b32_e32 v152, 16, v223
	v_and_b32_e32 v153, 0xffff0000, v223
	v_lshlrev_b32_e32 v168, 16, v231
	v_and_b32_e32 v169, 0xffff0000, v231
	v_max_f32_e32 v150, s100, v150
	v_max_f32_e32 v151, s100, v151
	v_max_f32_e32 v148, s100, v148
	v_max_f32_e32 v149, s100, v149
	v_max_f32_e32 v168, s100, v168
	v_max_f32_e32 v169, s100, v169
	v_max_f32_e32 v152, s100, v152
	v_max_f32_e32 v153, s100, v153
	v_rcp_f32_e32 v150, v150
	v_rcp_f32_e32 v151, v151
	v_rcp_f32_e32 v168, v168
	v_rcp_f32_e32 v169, v169
	s_nop 0
	v_pk_mul_f32 v[148:149], v[148:149], v[150:151]
	v_pk_mul_f32 v[152:153], v[152:153], v[168:169]
	v_pk_mul_f32 v[74:75], v[74:75], v[148:149]
	v_pk_mul_f32 v[76:77], v[76:77], v[152:153]
	global_load_dwordx4 v[216:219], v[140:141], off
	global_load_dwordx4 v[220:223], v[140:141], off offset:256
	global_load_dwordx4 v[224:227], v[140:141], off offset:2048
	global_load_dwordx4 v[228:231], v[140:141], off offset:2304
	s_waitcnt vmcnt(8)
; DI float bflo(unsigned w) { return __uint_as_float(w << 16); }
; DI float bfhi(unsigned w) { return __uint_as_float(w & 0xffff0000u); }
;     DI void operator()(Acc& acc, const Unit& u, int wr, int wc, int fr, int fq) const {
;     ...
;         bf16_t* base = proj + (size_t)(u.pm * 256 + wr * 64 + fr) * NPJ + C_GL + u.pn * 256 + wc * 32 + fq * 8;
;         {
;             u32x4 g[2][4][2];
; #pragma unroll
;             for (int ai = 0; ai < 2; ++ai)
; #pragma unroll
;                 for (int m = 0; m < 4; ++m)
; #pragma unroll
;                     for (int bj = 0; bj < 2; ++bj) g[ai][m][bj] = *(const u32x4*)(base + (size_t)(ai * 128 + m * 16) * NPJ + u.k * 1024 + bj * 128);
; #pragma unroll
;             for (int ai = 0; ai < 2; ++ai)
; #pragma unroll
;                 for (int m = 0; m < 4; ++m)
; #pragma unroll
;                     for (int bj = 0; bj < 2; ++bj) { const u32x4 q = g[ai][m][bj]; f32x4& v0 = acc[ai][bj][m][0]; f32x4& v1 = acc[ai][bj][m][1];
;                         v0[0] *= bflo(q.x); v0[1] *= bfhi(q.x); v0[2] *= bflo(q.y); v0[3] *= bfhi(q.y); v1[0] *= bflo(q.z); v1[1] *= bfhi(q.z); v1[2] *= bflo(q.w); v1[3] *= bfhi(q.w); }
	v_lshlrev_b32_e32 v148, 16, v184
	v_and_b32_e32 v149, 0xffff0000, v184
	v_lshlrev_b32_e32 v150, 16, v192
	v_and_b32_e32 v151, 0xffff0000, v192
	v_lshlrev_b32_e32 v152, 16, v185
	v_and_b32_e32 v153, 0xffff0000, v185
	v_lshlrev_b32_e32 v168, 16, v193
	v_and_b32_e32 v169, 0xffff0000, v193
	v_max_f32_e32 v150, s100, v150
	v_max_f32_e32 v151, s100, v151
	v_max_f32_e32 v148, s100, v148
	v_max_f32_e32 v149, s100, v149
	v_max_f32_e32 v168, s100, v168
	v_max_f32_e32 v169, s100, v169
	v_max_f32_e32 v152, s100, v152
	v_max_f32_e32 v153, s100, v153
	v_rcp_f32_e32 v150, v150
	v_rcp_f32_e32 v151, v151
	v_rcp_f32_e32 v168, v168
	v_rcp_f32_e32 v169, v169
	s_nop 0
	v_pk_mul_f32 v[148:149], v[148:149], v[150:151]
	v_pk_mul_f32 v[152:153], v[152:153], v[168:169]
	v_pk_mul_f32 v[86:87], v[86:87], v[148:149]
	v_pk_mul_f32 v[88:89], v[88:89], v[152:153]
	v_lshlrev_b32_e32 v176, 16, v186
	v_and_b32_e32 v177, 0xffff0000, v186
	v_lshlrev_b32_e32 v178, 16, v194
	v_and_b32_e32 v179, 0xffff0000, v194
	v_lshlrev_b32_e32 v180, 16, v187
	v_and_b32_e32 v181, 0xffff0000, v187
	v_lshlrev_b32_e32 v244, 16, v195
	v_and_b32_e32 v245, 0xffff0000, v195
	v_max_f32_e32 v178, s100, v178
	v_max_f32_e32 v179, s100, v179
	v_max_f32_e32 v176, s100, v176
	v_max_f32_e32 v177, s100, v177
	v_max_f32_e32 v244, s100, v244
	v_max_f32_e32 v245, s100, v245
	v_max_f32_e32 v180, s100, v180
	v_max_f32_e32 v181, s100, v181
	v_rcp_f32_e32 v178, v178
	v_rcp_f32_e32 v179, v179
	v_rcp_f32_e32 v244, v244
	v_rcp_f32_e32 v245, v245
	s_nop 0
	v_pk_mul_f32 v[176:177], v[176:177], v[178:179]
	v_pk_mul_f32 v[180:181], v[180:181], v[244:245]
	v_pk_mul_f32 v[78:79], v[78:79], v[176:177]
	v_pk_mul_f32 v[80:81], v[80:81], v[180:181]
	v_lshlrev_b32_e32 v176, 16, v188
	v_and_b32_e32 v177, 0xffff0000, v188
	v_lshlrev_b32_e32 v178, 16, v196
	v_and_b32_e32 v179, 0xffff0000, v196
	v_lshlrev_b32_e32 v180, 16, v189
	v_and_b32_e32 v181, 0xffff0000, v189
	v_lshlrev_b32_e32 v244, 16, v197
	v_and_b32_e32 v245, 0xffff0000, v197
	v_max_f32_e32 v178, s100, v178
	v_max_f32_e32 v179, s100, v179
	v_max_f32_e32 v176, s100, v176
	v_max_f32_e32 v177, s100, v177
	v_max_f32_e32 v244, s100, v244
	v_max_f32_e32 v245, s100, v245
	v_max_f32_e32 v180, s100, v180
	v_max_f32_e32 v181, s100, v181
	v_rcp_f32_e32 v178, v178
	v_rcp_f32_e32 v179, v179
	v_rcp_f32_e32 v244, v244
	v_rcp_f32_e32 v245, v245
	s_nop 0
	v_pk_mul_f32 v[176:177], v[176:177], v[178:179]
	v_pk_mul_f32 v[180:181], v[180:181], v[244:245]
	v_pk_mul_f32 v[70:71], v[70:71], v[176:177]
	v_pk_mul_f32 v[72:73], v[72:73], v[180:181]
	v_lshlrev_b32_e32 v148, 16, v190
	v_and_b32_e32 v149, 0xffff0000, v190
	v_lshlrev_b32_e32 v150, 16, v198
	v_and_b32_e32 v151, 0xffff0000, v198
	v_lshlrev_b32_e32 v152, 16, v191
	v_and_b32_e32 v153, 0xffff0000, v191
	v_lshlrev_b32_e32 v168, 16, v199
	v_and_b32_e32 v169, 0xffff0000, v199
	v_max_f32_e32 v150, s100, v150
	v_max_f32_e32 v151, s100, v151
	v_max_f32_e32 v148, s100, v148
	v_max_f32_e32 v149, s100, v149
	v_max_f32_e32 v168, s100, v168
	v_max_f32_e32 v169, s100, v169
	v_max_f32_e32 v152, s100, v152
	v_max_f32_e32 v153, s100, v153
	v_rcp_f32_e32 v150, v150
	v_rcp_f32_e32 v151, v151
	v_rcp_f32_e32 v168, v168
	v_rcp_f32_e32 v169, v169
	s_nop 0
	v_pk_mul_f32 v[148:149], v[148:149], v[150:151]
	v_pk_mul_f32 v[152:153], v[152:153], v[168:169]
	v_pk_mul_f32 v[66:67], v[66:67], v[148:149]
	v_pk_mul_f32 v[68:69], v[68:69], v[152:153]
	global_load_dwordx4 v[184:187], v[142:143], off
	global_load_dwordx4 v[188:191], v[142:143], off offset:256
	global_load_dwordx4 v[192:195], v[142:143], off offset:2048
	global_load_dwordx4 v[196:199], v[142:143], off offset:2304
	s_waitcnt vmcnt(8)
	v_lshlrev_b32_e32 v148, 16, v200
	v_and_b32_e32 v149, 0xffff0000, v200
	v_lshlrev_b32_e32 v150, 16, v208
	v_and_b32_e32 v151, 0xffff0000, v208
	v_lshlrev_b32_e32 v152, 16, v201
	v_and_b32_e32 v153, 0xffff0000, v201
	v_lshlrev_b32_e32 v168, 16, v209
	v_and_b32_e32 v169, 0xffff0000, v209
	v_max_f32_e32 v150, s100, v150
	v_max_f32_e32 v151, s100, v151
	v_max_f32_e32 v148, s100, v148
	v_max_f32_e32 v149, s100, v149
	v_max_f32_e32 v168, s100, v168
	v_max_f32_e32 v169, s100, v169
	v_max_f32_e32 v152, s100, v152
	v_max_f32_e32 v153, s100, v153
	v_rcp_f32_e32 v150, v150
	v_rcp_f32_e32 v151, v151
	v_rcp_f32_e32 v168, v168
	v_rcp_f32_e32 v169, v169
	s_nop 0
	v_pk_mul_f32 v[148:149], v[148:149], v[150:151]
	v_pk_mul_f32 v[152:153], v[152:153], v[168:169]
	v_pk_mul_f32 v[62:63], v[62:63], v[148:149]
	v_pk_mul_f32 v[64:65], v[64:65], v[152:153]
	v_lshlrev_b32_e32 v176, 16, v202
	v_and_b32_e32 v177, 0xffff0000, v202
	v_lshlrev_b32_e32 v178, 16, v210
	v_and_b32_e32 v179, 0xffff0000, v210
	v_lshlrev_b32_e32 v180, 16, v203
	v_and_b32_e32 v181, 0xffff0000, v203
	v_lshlrev_b32_e32 v244, 16, v211
	v_and_b32_e32 v245, 0xffff0000, v211
	v_max_f32_e32 v178, s100, v178
	v_max_f32_e32 v179, s100, v179
	v_max_f32_e32 v176, s100, v176
	v_max_f32_e32 v177, s100, v177
	v_max_f32_e32 v244, s100, v244
	v_max_f32_e32 v245, s100, v245
	v_max_f32_e32 v180, s100, v180
	v_max_f32_e32 v181, s100, v181
	v_rcp_f32_e32 v178, v178
	v_rcp_f32_e32 v179, v179
	v_rcp_f32_e32 v244, v244
	v_rcp_f32_e32 v245, v245
	s_nop 0
	v_pk_mul_f32 v[176:177], v[176:177], v[178:179]
	v_pk_mul_f32 v[180:181], v[180:181], v[244:245]
	v_pk_mul_f32 v[58:59], v[58:59], v[176:177]
	v_pk_mul_f32 v[60:61], v[60:61], v[180:181]
	v_lshlrev_b32_e32 v176, 16, v204
	v_and_b32_e32 v177, 0xffff0000, v204
	v_lshlrev_b32_e32 v178, 16, v212
	v_and_b32_e32 v179, 0xffff0000, v212
	v_lshlrev_b32_e32 v180, 16, v205
	v_and_b32_e32 v181, 0xffff0000, v205
	v_lshlrev_b32_e32 v244, 16, v213
	v_and_b32_e32 v245, 0xffff0000, v213
	v_max_f32_e32 v178, s100, v178
; DI float bflo(unsigned w) { return __uint_as_float(w << 16); }
; DI float bfhi(unsigned w) { return __uint_as_float(w & 0xffff0000u); }
;     DI void operator()(Acc& acc, const Unit& u, int wr, int wc, int fr, int fq) const {
;     ...
;         bf16_t* base = proj + (size_t)(u.pm * 256 + wr * 64 + fr) * NPJ + C_GL + u.pn * 256 + wc * 32 + fq * 8;
;         {
;             u32x4 g[2][4][2];
; #pragma unroll
;             for (int ai = 0; ai < 2; ++ai)
; #pragma unroll
;                 for (int m = 0; m < 4; ++m)
; #pragma unroll
;                     for (int bj = 0; bj < 2; ++bj) g[ai][m][bj] = *(const u32x4*)(base + (size_t)(ai * 128 + m * 16) * NPJ + u.k * 1024 + bj * 128);
; #pragma unroll
;             for (int ai = 0; ai < 2; ++ai)
; #pragma unroll
;                 for (int m = 0; m < 4; ++m)
; #pragma unroll
;                     for (int bj = 0; bj < 2; ++bj) { const u32x4 q = g[ai][m][bj]; f32x4& v0 = acc[ai][bj][m][0]; f32x4& v1 = acc[ai][bj][m][1];
;                         v0[0] *= bflo(q.x); v0[1] *= bfhi(q.x); v0[2] *= bflo(q.y); v0[3] *= bfhi(q.y); v1[0] *= bflo(q.z); v1[1] *= bfhi(q.z); v1[2] *= bflo(q.w); v1[3] *= bfhi(q.w); }
	v_max_f32_e32 v179, s100, v179
	v_max_f32_e32 v176, s100, v176
	v_max_f32_e32 v177, s100, v177
	v_max_f32_e32 v244, s100, v244
	v_max_f32_e32 v245, s100, v245
	v_max_f32_e32 v180, s100, v180
	v_max_f32_e32 v181, s100, v181
	v_rcp_f32_e32 v178, v178
	v_rcp_f32_e32 v179, v179
	v_rcp_f32_e32 v244, v244
	v_rcp_f32_e32 v245, v245
	s_nop 0
	v_pk_mul_f32 v[176:177], v[176:177], v[178:179]
	v_pk_mul_f32 v[180:181], v[180:181], v[244:245]
	v_pk_mul_f32 v[50:51], v[50:51], v[176:177]
	v_pk_mul_f32 v[52:53], v[52:53], v[180:181]
	v_lshlrev_b32_e32 v148, 16, v206
	v_and_b32_e32 v149, 0xffff0000, v206
	v_lshlrev_b32_e32 v150, 16, v214
	v_and_b32_e32 v151, 0xffff0000, v214
	v_lshlrev_b32_e32 v152, 16, v207
	v_and_b32_e32 v153, 0xffff0000, v207
	v_lshlrev_b32_e32 v168, 16, v215
	v_and_b32_e32 v169, 0xffff0000, v215
	v_max_f32_e32 v150, s100, v150
	v_max_f32_e32 v151, s100, v151
	v_max_f32_e32 v148, s100, v148
	v_max_f32_e32 v149, s100, v149
	v_max_f32_e32 v168, s100, v168
	v_max_f32_e32 v169, s100, v169
	v_max_f32_e32 v152, s100, v152
	v_max_f32_e32 v153, s100, v153
	v_rcp_f32_e32 v150, v150
	v_rcp_f32_e32 v151, v151
	v_rcp_f32_e32 v168, v168
	v_rcp_f32_e32 v169, v169
	s_nop 0
	v_pk_mul_f32 v[148:149], v[148:149], v[150:151]
	v_pk_mul_f32 v[152:153], v[152:153], v[168:169]
	v_pk_mul_f32 v[42:43], v[42:43], v[148:149]
	v_pk_mul_f32 v[44:45], v[44:45], v[152:153]
	global_load_dwordx4 v[200:203], v[144:145], off
	global_load_dwordx4 v[204:207], v[144:145], off offset:256
	global_load_dwordx4 v[208:211], v[144:145], off offset:2048
	global_load_dwordx4 v[212:215], v[144:145], off offset:2304
	s_waitcnt vmcnt(8)
	v_lshlrev_b32_e32 v148, 16, v216
	v_and_b32_e32 v149, 0xffff0000, v216
	v_lshlrev_b32_e32 v150, 16, v224
	v_and_b32_e32 v151, 0xffff0000, v224
	v_lshlrev_b32_e32 v152, 16, v217
	v_and_b32_e32 v153, 0xffff0000, v217
	v_lshlrev_b32_e32 v168, 16, v225
	v_and_b32_e32 v169, 0xffff0000, v225
	v_max_f32_e32 v150, s100, v150
	v_max_f32_e32 v151, s100, v151
	v_max_f32_e32 v148, s100, v148
	v_max_f32_e32 v149, s100, v149
	v_max_f32_e32 v168, s100, v168
	v_max_f32_e32 v169, s100, v169
	v_max_f32_e32 v152, s100, v152
	v_max_f32_e32 v153, s100, v153
	v_rcp_f32_e32 v150, v150
	v_rcp_f32_e32 v151, v151
	v_rcp_f32_e32 v168, v168
	v_rcp_f32_e32 v169, v169
	s_nop 0
	v_pk_mul_f32 v[148:149], v[148:149], v[150:151]
	v_pk_mul_f32 v[152:153], v[152:153], v[168:169]
	v_pk_mul_f32 v[54:55], v[54:55], v[148:149]
	v_pk_mul_f32 v[56:57], v[56:57], v[152:153]
	v_lshlrev_b32_e32 v176, 16, v218
	v_and_b32_e32 v177, 0xffff0000, v218
	v_lshlrev_b32_e32 v178, 16, v226
	v_and_b32_e32 v179, 0xffff0000, v226
	v_lshlrev_b32_e32 v180, 16, v219
	v_and_b32_e32 v181, 0xffff0000, v219
	v_lshlrev_b32_e32 v244, 16, v227
	v_and_b32_e32 v245, 0xffff0000, v227
	v_max_f32_e32 v178, s100, v178
	v_max_f32_e32 v179, s100, v179
	v_max_f32_e32 v176, s100, v176
	v_max_f32_e32 v177, s100, v177
	v_max_f32_e32 v244, s100, v244
	v_max_f32_e32 v245, s100, v245
	v_max_f32_e32 v180, s100, v180
	v_max_f32_e32 v181, s100, v181
	v_rcp_f32_e32 v178, v178
	v_rcp_f32_e32 v179, v179
	v_rcp_f32_e32 v244, v244
	v_rcp_f32_e32 v245, v245
	s_nop 0
	v_pk_mul_f32 v[176:177], v[176:177], v[178:179]
	v_pk_mul_f32 v[180:181], v[180:181], v[244:245]
	v_pk_mul_f32 v[46:47], v[46:47], v[176:177]
	v_pk_mul_f32 v[48:49], v[48:49], v[180:181]
	v_lshlrev_b32_e32 v176, 16, v220
	v_and_b32_e32 v177, 0xffff0000, v220
	v_lshlrev_b32_e32 v178, 16, v228
	v_and_b32_e32 v179, 0xffff0000, v228
	v_lshlrev_b32_e32 v180, 16, v221
	v_and_b32_e32 v181, 0xffff0000, v221
	v_lshlrev_b32_e32 v244, 16, v229
	v_and_b32_e32 v245, 0xffff0000, v229
	v_max_f32_e32 v178, s100, v178
	v_max_f32_e32 v179, s100, v179
	v_max_f32_e32 v176, s100, v176
	v_max_f32_e32 v177, s100, v177
	v_max_f32_e32 v244, s100, v244
	v_max_f32_e32 v245, s100, v245
	v_max_f32_e32 v180, s100, v180
	v_max_f32_e32 v181, s100, v181
	v_rcp_f32_e32 v178, v178
	v_rcp_f32_e32 v179, v179
	v_rcp_f32_e32 v244, v244
	v_rcp_f32_e32 v245, v245
	s_nop 0
	v_pk_mul_f32 v[176:177], v[176:177], v[178:179]
	v_pk_mul_f32 v[180:181], v[180:181], v[244:245]
	v_pk_mul_f32 v[34:35], v[34:35], v[176:177]
	v_pk_mul_f32 v[36:37], v[36:37], v[180:181]
	v_lshlrev_b32_e32 v148, 16, v222
	v_and_b32_e32 v149, 0xffff0000, v222
	v_lshlrev_b32_e32 v150, 16, v230
	v_and_b32_e32 v151, 0xffff0000, v230
	v_lshlrev_b32_e32 v152, 16, v223
	v_and_b32_e32 v153, 0xffff0000, v223
	v_lshlrev_b32_e32 v168, 16, v231
	v_and_b32_e32 v169, 0xffff0000, v231
	v_max_f32_e32 v150, s100, v150
	v_max_f32_e32 v151, s100, v151
	v_max_f32_e32 v148, s100, v148
	v_max_f32_e32 v149, s100, v149
	v_max_f32_e32 v168, s100, v168
	v_max_f32_e32 v169, s100, v169
	v_max_f32_e32 v152, s100, v152
	v_max_f32_e32 v153, s100, v153
	v_rcp_f32_e32 v150, v150
	v_rcp_f32_e32 v151, v151
	v_rcp_f32_e32 v168, v168
	v_rcp_f32_e32 v169, v169
	s_nop 0
	v_pk_mul_f32 v[148:149], v[148:149], v[150:151]
	v_pk_mul_f32 v[152:153], v[152:153], v[168:169]
	v_pk_mul_f32 v[26:27], v[26:27], v[148:149]
	v_pk_mul_f32 v[28:29], v[28:29], v[152:153]
	s_waitcnt vmcnt(4)
; DI float bflo(unsigned w) { return __uint_as_float(w << 16); }
; DI float bfhi(unsigned w) { return __uint_as_float(w & 0xffff0000u); }
;     DI void operator()(Acc& acc, const Unit& u, int wr, int wc, int fr, int fq) const {
;     ...
;         bf16_t* base = proj + (size_t)(u.pm * 256 + wr * 64 + fr) * NPJ + C_GL + u.pn * 256 + wc * 32 + fq * 8;
;         {
;             u32x4 g[2][4][2];
; #pragma unroll
;             for (int ai = 0; ai < 2; ++ai)
; #pragma unroll
;                 for (int m = 0; m < 4; ++m)
; #pragma unroll
;                     for (int bj = 0; bj < 2; ++bj) g[ai][m][bj] = *(const u32x4*)(base + (size_t)(ai * 128 + m * 16) * NPJ + u.k * 1024 + bj * 128);
; #pragma unroll
;             for (int ai = 0; ai < 2; ++ai)
; #pragma unroll
;                 for (int m = 0; m < 4; ++m)
; #pragma unroll
;                     for (int bj = 0; bj < 2; ++bj) { const u32x4 q = g[ai][m][bj]; f32x4& v0 = acc[ai][bj][m][0]; f32x4& v1 = acc[ai][bj][m][1];
;                         v0[0] *= bflo(q.x); v0[1] *= bfhi(q.x); v0[2] *= bflo(q.y); v0[3] *= bfhi(q.y); v1[0] *= bflo(q.z); v1[1] *= bfhi(q.z); v1[2] *= bflo(q.w); v1[3] *= bfhi(q.w); }
	v_lshlrev_b32_e32 v148, 16, v184
	v_and_b32_e32 v149, 0xffff0000, v184
	v_lshlrev_b32_e32 v150, 16, v192
	v_and_b32_e32 v151, 0xffff0000, v192
	v_lshlrev_b32_e32 v152, 16, v185
	v_and_b32_e32 v153, 0xffff0000, v185
	v_lshlrev_b32_e32 v168, 16, v193
	v_and_b32_e32 v169, 0xffff0000, v193
	v_max_f32_e32 v150, s100, v150
	v_max_f32_e32 v151, s100, v151
	v_max_f32_e32 v148, s100, v148
	v_max_f32_e32 v149, s100, v149
	v_max_f32_e32 v168, s100, v168
	v_max_f32_e32 v169, s100, v169
	v_max_f32_e32 v152, s100, v152
	v_max_f32_e32 v153, s100, v153
	v_rcp_f32_e32 v150, v150
	v_rcp_f32_e32 v151, v151
	v_rcp_f32_e32 v168, v168
	v_rcp_f32_e32 v169, v169
	s_nop 0
	v_pk_mul_f32 v[148:149], v[148:149], v[150:151]
	v_pk_mul_f32 v[152:153], v[152:153], v[168:169]
	v_pk_mul_f32 v[38:39], v[38:39], v[148:149]
	v_pk_mul_f32 v[40:41], v[40:41], v[152:153]
	v_lshlrev_b32_e32 v176, 16, v186
	v_and_b32_e32 v177, 0xffff0000, v186
	v_lshlrev_b32_e32 v178, 16, v194
	v_and_b32_e32 v179, 0xffff0000, v194
	v_lshlrev_b32_e32 v180, 16, v187
	v_and_b32_e32 v181, 0xffff0000, v187
	v_lshlrev_b32_e32 v244, 16, v195
	v_and_b32_e32 v245, 0xffff0000, v195
	v_max_f32_e32 v178, s100, v178
	v_max_f32_e32 v179, s100, v179
	v_max_f32_e32 v176, s100, v176
	v_max_f32_e32 v177, s100, v177
	v_max_f32_e32 v244, s100, v244
	v_max_f32_e32 v245, s100, v245
	v_max_f32_e32 v180, s100, v180
	v_max_f32_e32 v181, s100, v181
	v_rcp_f32_e32 v178, v178
	v_rcp_f32_e32 v179, v179
	v_rcp_f32_e32 v244, v244
	v_rcp_f32_e32 v245, v245
	s_nop 0
	v_pk_mul_f32 v[176:177], v[176:177], v[178:179]
	v_pk_mul_f32 v[180:181], v[180:181], v[244:245]
	v_pk_mul_f32 v[30:31], v[30:31], v[176:177]
	v_pk_mul_f32 v[32:33], v[32:33], v[180:181]
	v_lshlrev_b32_e32 v176, 16, v188
	v_and_b32_e32 v177, 0xffff0000, v188
	v_lshlrev_b32_e32 v178, 16, v196
	v_and_b32_e32 v179, 0xffff0000, v196
	v_lshlrev_b32_e32 v180, 16, v189
	v_and_b32_e32 v181, 0xffff0000, v189
	v_lshlrev_b32_e32 v244, 16, v197
	v_and_b32_e32 v245, 0xffff0000, v197
	v_max_f32_e32 v178, s100, v178
	v_max_f32_e32 v179, s100, v179
	v_max_f32_e32 v176, s100, v176
	v_max_f32_e32 v177, s100, v177
	v_max_f32_e32 v244, s100, v244
	v_max_f32_e32 v245, s100, v245
	v_max_f32_e32 v180, s100, v180
	v_max_f32_e32 v181, s100, v181
	v_rcp_f32_e32 v178, v178
	v_rcp_f32_e32 v179, v179
	v_rcp_f32_e32 v244, v244
	v_rcp_f32_e32 v245, v245
	s_nop 0
	v_pk_mul_f32 v[176:177], v[176:177], v[178:179]
	v_pk_mul_f32 v[180:181], v[180:181], v[244:245]
	v_pk_mul_f32 v[18:19], v[18:19], v[176:177]
	v_pk_mul_f32 v[20:21], v[20:21], v[180:181]
	v_lshlrev_b32_e32 v148, 16, v190
	v_and_b32_e32 v149, 0xffff0000, v190
	v_lshlrev_b32_e32 v150, 16, v198
	v_and_b32_e32 v151, 0xffff0000, v198
	v_lshlrev_b32_e32 v152, 16, v191
	v_and_b32_e32 v153, 0xffff0000, v191
	v_lshlrev_b32_e32 v168, 16, v199
	v_and_b32_e32 v169, 0xffff0000, v199
	v_max_f32_e32 v150, s100, v150
	v_max_f32_e32 v151, s100, v151
	v_max_f32_e32 v148, s100, v148
	v_max_f32_e32 v149, s100, v149
	v_max_f32_e32 v168, s100, v168
	v_max_f32_e32 v169, s100, v169
	v_max_f32_e32 v152, s100, v152
	v_max_f32_e32 v153, s100, v153
	v_rcp_f32_e32 v150, v150
	v_rcp_f32_e32 v151, v151
	v_rcp_f32_e32 v168, v168
	v_rcp_f32_e32 v169, v169
	s_nop 0
	v_pk_mul_f32 v[148:149], v[148:149], v[150:151]
	v_pk_mul_f32 v[152:153], v[152:153], v[168:169]
	v_pk_mul_f32 v[10:11], v[10:11], v[148:149]
	v_pk_mul_f32 v[12:13], v[12:13], v[152:153]
	s_waitcnt vmcnt(0)
	v_lshlrev_b32_e32 v148, 16, v200
	v_and_b32_e32 v149, 0xffff0000, v200
	v_lshlrev_b32_e32 v150, 16, v208
	v_and_b32_e32 v151, 0xffff0000, v208
	v_lshlrev_b32_e32 v152, 16, v201
	v_and_b32_e32 v153, 0xffff0000, v201
	v_lshlrev_b32_e32 v168, 16, v209
	v_and_b32_e32 v169, 0xffff0000, v209
	v_max_f32_e32 v150, s100, v150
	v_max_f32_e32 v151, s100, v151
	v_max_f32_e32 v148, s100, v148
	v_max_f32_e32 v149, s100, v149
	v_max_f32_e32 v168, s100, v168
	v_max_f32_e32 v169, s100, v169
	v_max_f32_e32 v152, s100, v152
	v_max_f32_e32 v153, s100, v153
	v_rcp_f32_e32 v150, v150
	v_rcp_f32_e32 v151, v151
	v_rcp_f32_e32 v168, v168
	v_rcp_f32_e32 v169, v169
	s_nop 0
	v_pk_mul_f32 v[148:149], v[148:149], v[150:151]
	v_pk_mul_f32 v[152:153], v[152:153], v[168:169]
	v_pk_mul_f32 v[22:23], v[22:23], v[148:149]
	v_pk_mul_f32 v[24:25], v[24:25], v[152:153]
	v_lshlrev_b32_e32 v176, 16, v202
	v_and_b32_e32 v177, 0xffff0000, v202
	v_lshlrev_b32_e32 v178, 16, v210
	v_and_b32_e32 v179, 0xffff0000, v210
	v_lshlrev_b32_e32 v180, 16, v203
	v_and_b32_e32 v181, 0xffff0000, v203
	v_lshlrev_b32_e32 v244, 16, v211
	v_and_b32_e32 v245, 0xffff0000, v211
	v_max_f32_e32 v178, s100, v178
	v_max_f32_e32 v179, s100, v179
	v_max_f32_e32 v176, s100, v176
	v_max_f32_e32 v177, s100, v177
	v_max_f32_e32 v244, s100, v244
	v_max_f32_e32 v245, s100, v245
	v_max_f32_e32 v180, s100, v180
	v_max_f32_e32 v181, s100, v181
	v_rcp_f32_e32 v178, v178
	v_rcp_f32_e32 v179, v179
	v_rcp_f32_e32 v244, v244
	v_rcp_f32_e32 v245, v245
	s_nop 0
	v_pk_mul_f32 v[176:177], v[176:177], v[178:179]
	v_pk_mul_f32 v[180:181], v[180:181], v[244:245]
	v_pk_mul_f32 v[14:15], v[14:15], v[176:177]
	v_pk_mul_f32 v[16:17], v[16:17], v[180:181]
	v_lshlrev_b32_e32 v176, 16, v204
	v_and_b32_e32 v177, 0xffff0000, v204
	v_lshlrev_b32_e32 v178, 16, v212
	v_and_b32_e32 v179, 0xffff0000, v212
	v_lshlrev_b32_e32 v180, 16, v205
	v_and_b32_e32 v181, 0xffff0000, v205
	v_lshlrev_b32_e32 v244, 16, v213
	v_and_b32_e32 v245, 0xffff0000, v213
	v_max_f32_e32 v178, s100, v178
	v_max_f32_e32 v179, s100, v179
	v_max_f32_e32 v176, s100, v176
	v_max_f32_e32 v177, s100, v177
	v_max_f32_e32 v244, s100, v244
	v_max_f32_e32 v245, s100, v245
	v_max_f32_e32 v180, s100, v180
	v_max_f32_e32 v181, s100, v181
	v_rcp_f32_e32 v178, v178
	v_rcp_f32_e32 v179, v179
	v_rcp_f32_e32 v244, v244
	v_rcp_f32_e32 v245, v245
	s_nop 0
	v_pk_mul_f32 v[176:177], v[176:177], v[178:179]
	v_pk_mul_f32 v[180:181], v[180:181], v[244:245]
	v_pk_mul_f32 v[6:7], v[6:7], v[176:177]
	v_pk_mul_f32 v[8:9], v[8:9], v[180:181]
	v_lshlrev_b32_e32 v148, 16, v206
	v_and_b32_e32 v149, 0xffff0000, v206
	v_lshlrev_b32_e32 v150, 16, v214
	v_and_b32_e32 v151, 0xffff0000, v214
	v_lshlrev_b32_e32 v152, 16, v207
	v_and_b32_e32 v153, 0xffff0000, v207
	v_lshlrev_b32_e32 v168, 16, v215
	v_and_b32_e32 v169, 0xffff0000, v215
	v_max_f32_e32 v150, s100, v150
	v_max_f32_e32 v151, s100, v151
	v_max_f32_e32 v148, s100, v148
	v_max_f32_e32 v149, s100, v149
	v_max_f32_e32 v168, s100, v168
	v_max_f32_e32 v169, s100, v169
	v_max_f32_e32 v152, s100, v152
	v_max_f32_e32 v153, s100, v153
	v_rcp_f32_e32 v150, v150
	v_rcp_f32_e32 v151, v151
	v_rcp_f32_e32 v168, v168
	v_rcp_f32_e32 v169, v169
	s_nop 0
	v_pk_mul_f32 v[148:149], v[148:149], v[150:151]
	v_pk_mul_f32 v[152:153], v[152:153], v[168:169]
	v_pk_mul_f32 v[2:3], v[2:3], v[148:149]
	v_pk_mul_f32 v[4:5], v[4:5], v[152:153]
	s_branch .Lup6_tail
; DI float bflo(unsigned w) { return __uint_as_float(w << 16); }
; DI float bfhi(unsigned w) { return __uint_as_float(w & 0xffff0000u); }
; DI u32x4 pack8(f32x4 a, f32x4 b) { u32x4 w; w.x = pk2(a[0], a[1]); w.y = pk2(a[2], a[3]); w.z = pk2(b[0], b[1]); w.w = pk2(b[2], b[3]); return w; }
;     DI void operator()(Acc& acc, const Unit& u, int wr, int wc, int fr, int fq) const {
;     ...
;             for (int ai = 0; ai < 2; ++ai)
; #pragma unroll
;                 for (int m = 0; m < 4; ++m)
; #pragma unroll
;                     for (int bj = 0; bj < 2; ++bj) { const u32x4 q = g[ai][m][bj]; f32x4& v0 = acc[ai][bj][m][0]; f32x4& v1 = acc[ai][bj][m][1];
;                         v0[0] *= bflo(q.x); v0[1] *= bfhi(q.x); v0[2] *= bflo(q.y); v0[3] *= bfhi(q.y); v1[0] *= bflo(q.z); v1[1] *= bfhi(q.z); v1[2] *= bflo(q.w); v1[3] *= bfhi(q.w); }
;         }
;         if (u.k > 0) {
;             u32x4 g[2][4][2];
; #pragma unroll
;             for (int ai = 0; ai < 2; ++ai)
; #pragma unroll
;                 for (int m = 0; m < 4; ++m)
; #pragma unroll
;                     for (int bj = 0; bj < 2; ++bj) g[ai][m][bj] = *(const u32x4*)(base + (size_t)(ai * 128 + m * 16) * NPJ + bj * 128);
; #pragma unroll
;             for (int ai = 0; ai < 2; ++ai)
; #pragma unroll
;                 for (int m = 0; m < 4; ++m)
; #pragma unroll
;                     for (int bj = 0; bj < 2; ++bj) { const u32x4 q = g[ai][m][bj]; f32x4& v0 = acc[ai][bj][m][0]; f32x4& v1 = acc[ai][bj][m][1];
;                         v0[0] += bflo(q.x); v0[1] += bfhi(q.x); v0[2] += bflo(q.y); v0[3] += bfhi(q.y); v1[0] += bflo(q.z); v1[1] += bfhi(q.z); v1[2] += bflo(q.w); v1[3] += bfhi(q.w); }
;         }
;         if (!dry) {
; #pragma unroll
;             for (int ai = 0; ai < 2; ++ai)
; #pragma unroll
;                 for (int m = 0; m < 4; ++m)
; #pragma unroll
;                     for (int bj = 0; bj < 2; ++bj) *(u32x4*)(base + (size_t)(ai * 128 + m * 16) * NPJ + bj * 128) = pack8(acc[ai][bj][m][0], acc[ai][bj][m][1]);
.Lup6_final:
	global_load_dwordx4 v[184:187], v[130:131], off
	global_load_dwordx4 v[188:191], v[130:131], off offset:256
	global_load_dwordx4 v[192:195], v[132:133], off
	global_load_dwordx4 v[196:199], v[132:133], off offset:256
	global_load_dwordx4 v[200:203], v[134:135], off
	global_load_dwordx4 v[204:207], v[134:135], off offset:256
	global_load_dwordx4 v[208:211], v[136:137], off
	global_load_dwordx4 v[212:215], v[136:137], off offset:256
	global_load_dwordx4 v[216:219], v[138:139], off
	global_load_dwordx4 v[220:223], v[138:139], off offset:256
	global_load_dwordx4 v[224:227], v[140:141], off
	global_load_dwordx4 v[228:231], v[140:141], off offset:256
	s_waitcnt vmcnt(10)
	v_lshlrev_b32_e32 v148, 16, v184
	v_and_b32_e32 v149, 0xffff0000, v184
	v_lshlrev_b32_e32 v150, 16, v185
	v_and_b32_e32 v151, 0xffff0000, v185
	v_lshlrev_b32_e32 v152, 16, v186
	v_and_b32_e32 v153, 0xffff0000, v186
	v_lshlrev_b32_e32 v168, 16, v187
	v_and_b32_e32 v169, 0xffff0000, v187
	v_max_f32_e32 v148, s100, v148
	v_max_f32_e32 v149, s100, v149
	v_max_f32_e32 v150, s100, v150
	v_max_f32_e32 v151, s100, v151
	v_max_f32_e32 v152, s100, v152
	v_max_f32_e32 v153, s100, v153
	v_max_f32_e32 v168, s100, v168
	v_max_f32_e32 v169, s100, v169
	v_pk_mul_f32 v[126:127], v[126:127], v[148:149]
	v_pk_mul_f32 v[128:129], v[128:129], v[150:151]
	v_pk_mul_f32 v[122:123], v[122:123], v[152:153]
	v_pk_mul_f32 v[124:125], v[124:125], v[168:169]
	v_cvt_pk_bf16_f32 v184, v126, v127
	v_cvt_pk_bf16_f32 v185, v128, v129
	v_cvt_pk_bf16_f32 v186, v122, v123
	v_cvt_pk_bf16_f32 v187, v124, v125
	v_lshlrev_b32_e32 v176, 16, v188
	v_and_b32_e32 v177, 0xffff0000, v188
	v_lshlrev_b32_e32 v178, 16, v189
	v_and_b32_e32 v179, 0xffff0000, v189
	v_lshlrev_b32_e32 v180, 16, v190
	v_and_b32_e32 v181, 0xffff0000, v190
	v_lshlrev_b32_e32 v244, 16, v191
	v_and_b32_e32 v245, 0xffff0000, v191
	v_max_f32_e32 v176, s100, v176
	v_max_f32_e32 v177, s100, v177
	v_max_f32_e32 v178, s100, v178
	v_max_f32_e32 v179, s100, v179
	v_max_f32_e32 v180, s100, v180
	v_max_f32_e32 v181, s100, v181
	v_max_f32_e32 v244, s100, v244
	v_max_f32_e32 v245, s100, v245
	v_pk_mul_f32 v[114:115], v[114:115], v[176:177]
	v_pk_mul_f32 v[116:117], v[116:117], v[178:179]
	v_pk_mul_f32 v[110:111], v[110:111], v[180:181]
	v_pk_mul_f32 v[112:113], v[112:113], v[244:245]
	v_cvt_pk_bf16_f32 v188, v114, v115
	v_cvt_pk_bf16_f32 v189, v116, v117
	v_cvt_pk_bf16_f32 v190, v110, v111
	v_cvt_pk_bf16_f32 v191, v112, v113
	global_store_dwordx4 v[130:131], v[184:187], off offset:-4096
	global_store_dwordx4 v[130:131], v[188:191], off offset:-3840
	s_nop 1
	global_load_dwordx4 v[184:187], v[142:143], off
	global_load_dwordx4 v[188:191], v[142:143], off offset:256
	s_waitcnt vmcnt(12)
	v_lshlrev_b32_e32 v148, 16, v192
	v_and_b32_e32 v149, 0xffff0000, v192
	v_lshlrev_b32_e32 v150, 16, v193
	v_and_b32_e32 v151, 0xffff0000, v193
	v_lshlrev_b32_e32 v152, 16, v194
	v_and_b32_e32 v153, 0xffff0000, v194
	v_lshlrev_b32_e32 v168, 16, v195
	v_and_b32_e32 v169, 0xffff0000, v195
	v_max_f32_e32 v148, s100, v148
	v_max_f32_e32 v149, s100, v149
	v_max_f32_e32 v150, s100, v150
	v_max_f32_e32 v151, s100, v151
	v_max_f32_e32 v152, s100, v152
	v_max_f32_e32 v153, s100, v153
	v_max_f32_e32 v168, s100, v168
	v_max_f32_e32 v169, s100, v169
	v_pk_mul_f32 v[118:119], v[118:119], v[148:149]
	v_pk_mul_f32 v[120:121], v[120:121], v[150:151]
	v_pk_mul_f32 v[106:107], v[106:107], v[152:153]
	v_pk_mul_f32 v[108:109], v[108:109], v[168:169]
	v_cvt_pk_bf16_f32 v192, v118, v119
	v_cvt_pk_bf16_f32 v193, v120, v121
	v_cvt_pk_bf16_f32 v194, v106, v107
	v_cvt_pk_bf16_f32 v195, v108, v109
	v_lshlrev_b32_e32 v176, 16, v196
	v_and_b32_e32 v177, 0xffff0000, v196
	v_lshlrev_b32_e32 v178, 16, v197
	v_and_b32_e32 v179, 0xffff0000, v197
	v_lshlrev_b32_e32 v180, 16, v198
	v_and_b32_e32 v181, 0xffff0000, v198
	v_lshlrev_b32_e32 v244, 16, v199
	v_and_b32_e32 v245, 0xffff0000, v199
	v_max_f32_e32 v176, s100, v176
	v_max_f32_e32 v177, s100, v177
	v_max_f32_e32 v178, s100, v178
	v_max_f32_e32 v179, s100, v179
	v_max_f32_e32 v180, s100, v180
	v_max_f32_e32 v181, s100, v181
	v_max_f32_e32 v244, s100, v244
	v_max_f32_e32 v245, s100, v245
	v_pk_mul_f32 v[98:99], v[98:99], v[176:177]
	v_pk_mul_f32 v[100:101], v[100:101], v[178:179]
	v_pk_mul_f32 v[90:91], v[90:91], v[180:181]
	v_pk_mul_f32 v[92:93], v[92:93], v[244:245]
	v_cvt_pk_bf16_f32 v196, v98, v99
	v_cvt_pk_bf16_f32 v197, v100, v101
	v_cvt_pk_bf16_f32 v198, v90, v91
	v_cvt_pk_bf16_f32 v199, v92, v93
	global_store_dwordx4 v[132:133], v[192:195], off offset:-4096
	global_store_dwordx4 v[132:133], v[196:199], off offset:-3840
	s_nop 1
	global_load_dwordx4 v[192:195], v[144:145], off
	global_load_dwordx4 v[196:199], v[144:145], off offset:256
	s_waitcnt vmcnt(14)
; DI float bflo(unsigned w) { return __uint_as_float(w << 16); }
; DI float bfhi(unsigned w) { return __uint_as_float(w & 0xffff0000u); }
; DI u32x4 pack8(f32x4 a, f32x4 b) { u32x4 w; w.x = pk2(a[0], a[1]); w.y = pk2(a[2], a[3]); w.z = pk2(b[0], b[1]); w.w = pk2(b[2], b[3]); return w; }
;     DI void operator()(Acc& acc, const Unit& u, int wr, int wc, int fr, int fq) const {
;     ...
;             for (int ai = 0; ai < 2; ++ai)
; #pragma unroll
;                 for (int m = 0; m < 4; ++m)
; #pragma unroll
;                     for (int bj = 0; bj < 2; ++bj) { const u32x4 q = g[ai][m][bj]; f32x4& v0 = acc[ai][bj][m][0]; f32x4& v1 = acc[ai][bj][m][1];
;                         v0[0] *= bflo(q.x); v0[1] *= bfhi(q.x); v0[2] *= bflo(q.y); v0[3] *= bfhi(q.y); v1[0] *= bflo(q.z); v1[1] *= bfhi(q.z); v1[2] *= bflo(q.w); v1[3] *= bfhi(q.w); }
;         }
;         if (u.k > 0) {
;             u32x4 g[2][4][2];
; #pragma unroll
;             for (int ai = 0; ai < 2; ++ai)
; #pragma unroll
;                 for (int m = 0; m < 4; ++m)
; #pragma unroll
;                     for (int bj = 0; bj < 2; ++bj) g[ai][m][bj] = *(const u32x4*)(base + (size_t)(ai * 128 + m * 16) * NPJ + bj * 128);
; #pragma unroll
;             for (int ai = 0; ai < 2; ++ai)
; #pragma unroll
;                 for (int m = 0; m < 4; ++m)
; #pragma unroll
;                     for (int bj = 0; bj < 2; ++bj) { const u32x4 q = g[ai][m][bj]; f32x4& v0 = acc[ai][bj][m][0]; f32x4& v1 = acc[ai][bj][m][1];
;                         v0[0] += bflo(q.x); v0[1] += bfhi(q.x); v0[2] += bflo(q.y); v0[3] += bfhi(q.y); v1[0] += bflo(q.z); v1[1] += bfhi(q.z); v1[2] += bflo(q.w); v1[3] += bfhi(q.w); }
;         }
;         if (!dry) {
; #pragma unroll
;             for (int ai = 0; ai < 2; ++ai)
; #pragma unroll
;                 for (int m = 0; m < 4; ++m)
; #pragma unroll
;                     for (int bj = 0; bj < 2; ++bj) *(u32x4*)(base + (size_t)(ai * 128 + m * 16) * NPJ + bj * 128) = pack8(acc[ai][bj][m][0], acc[ai][bj][m][1]);
	v_lshlrev_b32_e32 v148, 16, v200
	v_and_b32_e32 v149, 0xffff0000, v200
	v_lshlrev_b32_e32 v150, 16, v201
	v_and_b32_e32 v151, 0xffff0000, v201
	v_lshlrev_b32_e32 v152, 16, v202
	v_and_b32_e32 v153, 0xffff0000, v202
	v_lshlrev_b32_e32 v168, 16, v203
	v_and_b32_e32 v169, 0xffff0000, v203
	v_max_f32_e32 v148, s100, v148
	v_max_f32_e32 v149, s100, v149
	v_max_f32_e32 v150, s100, v150
	v_max_f32_e32 v151, s100, v151
	v_max_f32_e32 v152, s100, v152
	v_max_f32_e32 v153, s100, v153
	v_max_f32_e32 v168, s100, v168
	v_max_f32_e32 v169, s100, v169
	v_pk_mul_f32 v[102:103], v[102:103], v[148:149]
	v_pk_mul_f32 v[104:105], v[104:105], v[150:151]
	v_pk_mul_f32 v[94:95], v[94:95], v[152:153]
	v_pk_mul_f32 v[96:97], v[96:97], v[168:169]
	v_cvt_pk_bf16_f32 v200, v102, v103
	v_cvt_pk_bf16_f32 v201, v104, v105
	v_cvt_pk_bf16_f32 v202, v94, v95
	v_cvt_pk_bf16_f32 v203, v96, v97
	v_lshlrev_b32_e32 v176, 16, v204
	v_and_b32_e32 v177, 0xffff0000, v204
	v_lshlrev_b32_e32 v178, 16, v205
	v_and_b32_e32 v179, 0xffff0000, v205
	v_lshlrev_b32_e32 v180, 16, v206
	v_and_b32_e32 v181, 0xffff0000, v206
	v_lshlrev_b32_e32 v244, 16, v207
	v_and_b32_e32 v245, 0xffff0000, v207
	v_max_f32_e32 v176, s100, v176
	v_max_f32_e32 v177, s100, v177
	v_max_f32_e32 v178, s100, v178
	v_max_f32_e32 v179, s100, v179
	v_max_f32_e32 v180, s100, v180
	v_max_f32_e32 v181, s100, v181
	v_max_f32_e32 v244, s100, v244
	v_max_f32_e32 v245, s100, v245
	v_pk_mul_f32 v[82:83], v[82:83], v[176:177]
	v_pk_mul_f32 v[84:85], v[84:85], v[178:179]
	v_pk_mul_f32 v[74:75], v[74:75], v[180:181]
	v_pk_mul_f32 v[76:77], v[76:77], v[244:245]
	v_cvt_pk_bf16_f32 v204, v82, v83
	v_cvt_pk_bf16_f32 v205, v84, v85
	v_cvt_pk_bf16_f32 v206, v74, v75
	v_cvt_pk_bf16_f32 v207, v76, v77
	global_store_dwordx4 v[134:135], v[200:203], off offset:-4096
	global_store_dwordx4 v[134:135], v[204:207], off offset:-3840
	s_waitcnt vmcnt(14)
	v_lshlrev_b32_e32 v148, 16, v208
	v_and_b32_e32 v149, 0xffff0000, v208
	v_lshlrev_b32_e32 v150, 16, v209
	v_and_b32_e32 v151, 0xffff0000, v209
	v_lshlrev_b32_e32 v152, 16, v210
	v_and_b32_e32 v153, 0xffff0000, v210
	v_lshlrev_b32_e32 v168, 16, v211
	v_and_b32_e32 v169, 0xffff0000, v211
	v_max_f32_e32 v148, s100, v148
	v_max_f32_e32 v149, s100, v149
	v_max_f32_e32 v150, s100, v150
	v_max_f32_e32 v151, s100, v151
	v_max_f32_e32 v152, s100, v152
	v_max_f32_e32 v153, s100, v153
	v_max_f32_e32 v168, s100, v168
	v_max_f32_e32 v169, s100, v169
	v_pk_mul_f32 v[86:87], v[86:87], v[148:149]
	v_pk_mul_f32 v[88:89], v[88:89], v[150:151]
	v_pk_mul_f32 v[78:79], v[78:79], v[152:153]
	v_pk_mul_f32 v[80:81], v[80:81], v[168:169]
	v_cvt_pk_bf16_f32 v208, v86, v87
	v_cvt_pk_bf16_f32 v209, v88, v89
	v_cvt_pk_bf16_f32 v210, v78, v79
	v_cvt_pk_bf16_f32 v211, v80, v81
	v_lshlrev_b32_e32 v176, 16, v212
	v_and_b32_e32 v177, 0xffff0000, v212
	v_lshlrev_b32_e32 v178, 16, v213
	v_and_b32_e32 v179, 0xffff0000, v213
	v_lshlrev_b32_e32 v180, 16, v214
	v_and_b32_e32 v181, 0xffff0000, v214
	v_lshlrev_b32_e32 v244, 16, v215
	v_and_b32_e32 v245, 0xffff0000, v215
	v_max_f32_e32 v176, s100, v176
	v_max_f32_e32 v177, s100, v177
	v_max_f32_e32 v178, s100, v178
	v_max_f32_e32 v179, s100, v179
	v_max_f32_e32 v180, s100, v180
	v_max_f32_e32 v181, s100, v181
	v_max_f32_e32 v244, s100, v244
	v_max_f32_e32 v245, s100, v245
	v_pk_mul_f32 v[70:71], v[70:71], v[176:177]
	v_pk_mul_f32 v[72:73], v[72:73], v[178:179]
	v_pk_mul_f32 v[66:67], v[66:67], v[180:181]
	v_pk_mul_f32 v[68:69], v[68:69], v[244:245]
	v_cvt_pk_bf16_f32 v212, v70, v71
	v_cvt_pk_bf16_f32 v213, v72, v73
	v_cvt_pk_bf16_f32 v214, v66, v67
	v_cvt_pk_bf16_f32 v215, v68, v69
	global_store_dwordx4 v[136:137], v[208:211], off offset:-4096
	global_store_dwordx4 v[136:137], v[212:215], off offset:-3840
	s_waitcnt vmcnt(14)
	v_lshlrev_b32_e32 v148, 16, v216
	v_and_b32_e32 v149, 0xffff0000, v216
	v_lshlrev_b32_e32 v150, 16, v217
	v_and_b32_e32 v151, 0xffff0000, v217
	v_lshlrev_b32_e32 v152, 16, v218
	v_and_b32_e32 v153, 0xffff0000, v218
	v_lshlrev_b32_e32 v168, 16, v219
	v_and_b32_e32 v169, 0xffff0000, v219
	v_max_f32_e32 v148, s100, v148
	v_max_f32_e32 v149, s100, v149
	v_max_f32_e32 v150, s100, v150
	v_max_f32_e32 v151, s100, v151
	v_max_f32_e32 v152, s100, v152
	v_max_f32_e32 v153, s100, v153
	v_max_f32_e32 v168, s100, v168
	v_max_f32_e32 v169, s100, v169
	v_pk_mul_f32 v[62:63], v[62:63], v[148:149]
	v_pk_mul_f32 v[64:65], v[64:65], v[150:151]
	v_pk_mul_f32 v[58:59], v[58:59], v[152:153]
	v_pk_mul_f32 v[60:61], v[60:61], v[168:169]
	v_cvt_pk_bf16_f32 v216, v62, v63
	v_cvt_pk_bf16_f32 v217, v64, v65
	v_cvt_pk_bf16_f32 v218, v58, v59
	v_cvt_pk_bf16_f32 v219, v60, v61
	v_lshlrev_b32_e32 v176, 16, v220
	v_and_b32_e32 v177, 0xffff0000, v220
	v_lshlrev_b32_e32 v178, 16, v221
	v_and_b32_e32 v179, 0xffff0000, v221
	v_lshlrev_b32_e32 v180, 16, v222
	v_and_b32_e32 v181, 0xffff0000, v222
	v_lshlrev_b32_e32 v244, 16, v223
	v_and_b32_e32 v245, 0xffff0000, v223
	v_max_f32_e32 v176, s100, v176
	v_max_f32_e32 v177, s100, v177
	v_max_f32_e32 v178, s100, v178
	v_max_f32_e32 v179, s100, v179
	v_max_f32_e32 v180, s100, v180
	v_max_f32_e32 v181, s100, v181
	v_max_f32_e32 v244, s100, v244
	v_max_f32_e32 v245, s100, v245
	v_pk_mul_f32 v[50:51], v[50:51], v[176:177]
	v_pk_mul_f32 v[52:53], v[52:53], v[178:179]
	v_pk_mul_f32 v[42:43], v[42:43], v[180:181]
	v_pk_mul_f32 v[44:45], v[44:45], v[244:245]
	v_cvt_pk_bf16_f32 v220, v50, v51
	v_cvt_pk_bf16_f32 v221, v52, v53
	v_cvt_pk_bf16_f32 v222, v42, v43
	v_cvt_pk_bf16_f32 v223, v44, v45
	global_store_dwordx4 v[138:139], v[216:219], off offset:-4096
	global_store_dwordx4 v[138:139], v[220:223], off offset:-3840
	s_waitcnt vmcnt(14)
; DI float bflo(unsigned w) { return __uint_as_float(w << 16); }
; DI float bfhi(unsigned w) { return __uint_as_float(w & 0xffff0000u); }
; template <class Epi, class Sched>
; DI void gemm_phase(LAS unsigned char* lds, const Sched& S, const Epi& E) {
;     ...
;         if (!has_next) break;
; #pragma unroll
;         for (int a = 0; a < 2; ++a)
; #pragma unroll
;             for (int b = 0; b < 2; ++b)
; #pragma unroll
;                 for (int m = 0; m < 4; ++m)
; #pragma unroll
;                     for (int n = 0; n < 2; ++n) acc[a][b][m][n] = (f32x4){0.f, 0.f, 0.f, 0.f};
;         cur = nxt; cA = nA; cB = nB; ++ui;
;         if (wr == 1) PG8_BAR;
;     DI void operator()(Acc& acc, const Unit& u, int wr, int wc, int fr, int fq) const {
;     ...
;             for (int ai = 0; ai < 2; ++ai)
; #pragma unroll
;                 for (int m = 0; m < 4; ++m)
; #pragma unroll
;                     for (int bj = 0; bj < 2; ++bj) { const u32x4 q = g[ai][m][bj]; f32x4& v0 = acc[ai][bj][m][0]; f32x4& v1 = acc[ai][bj][m][1];
;                         v0[0] *= bflo(q.x); v0[1] *= bfhi(q.x); v0[2] *= bflo(q.y); v0[3] *= bfhi(q.y); v1[0] *= bflo(q.z); v1[1] *= bfhi(q.z); v1[2] *= bflo(q.w); v1[3] *= bfhi(q.w); }
;         }
;         if (u.k > 0) {
;             u32x4 g[2][4][2];
; #pragma unroll
;             for (int ai = 0; ai < 2; ++ai)
; #pragma unroll
;                 for (int m = 0; m < 4; ++m)
; #pragma unroll
;                     for (int bj = 0; bj < 2; ++bj) g[ai][m][bj] = *(const u32x4*)(base + (size_t)(ai * 128 + m * 16) * NPJ + bj * 128);
; #pragma unroll
;             for (int ai = 0; ai < 2; ++ai)
; #pragma unroll
;                 for (int m = 0; m < 4; ++m)
; #pragma unroll
;                     for (int bj = 0; bj < 2; ++bj) { const u32x4 q = g[ai][m][bj]; f32x4& v0 = acc[ai][bj][m][0]; f32x4& v1 = acc[ai][bj][m][1];
;                         v0[0] += bflo(q.x); v0[1] += bfhi(q.x); v0[2] += bflo(q.y); v0[3] += bfhi(q.y); v1[0] += bflo(q.z); v1[1] += bfhi(q.z); v1[2] += bflo(q.w); v1[3] += bfhi(q.w); }
;         }
;         if (!dry) {
; #pragma unroll
;             for (int ai = 0; ai < 2; ++ai)
; #pragma unroll
;                 for (int m = 0; m < 4; ++m)
; #pragma unroll
;                     for (int bj = 0; bj < 2; ++bj) *(u32x4*)(base + (size_t)(ai * 128 + m * 16) * NPJ + bj * 128) = pack8(acc[ai][bj][m][0], acc[ai][bj][m][1]);
	v_lshlrev_b32_e32 v148, 16, v224
	v_and_b32_e32 v149, 0xffff0000, v224
	v_lshlrev_b32_e32 v150, 16, v225
	v_and_b32_e32 v151, 0xffff0000, v225
	v_lshlrev_b32_e32 v152, 16, v226
	v_and_b32_e32 v153, 0xffff0000, v226
	v_lshlrev_b32_e32 v168, 16, v227
	v_and_b32_e32 v169, 0xffff0000, v227
	v_max_f32_e32 v148, s100, v148
	v_max_f32_e32 v149, s100, v149
	v_max_f32_e32 v150, s100, v150
	v_max_f32_e32 v151, s100, v151
	v_max_f32_e32 v152, s100, v152
	v_max_f32_e32 v153, s100, v153
	v_max_f32_e32 v168, s100, v168
	v_max_f32_e32 v169, s100, v169
	v_pk_mul_f32 v[54:55], v[54:55], v[148:149]
	v_pk_mul_f32 v[56:57], v[56:57], v[150:151]
	v_pk_mul_f32 v[46:47], v[46:47], v[152:153]
	v_pk_mul_f32 v[48:49], v[48:49], v[168:169]
	v_cvt_pk_bf16_f32 v224, v54, v55
	v_cvt_pk_bf16_f32 v225, v56, v57
	v_cvt_pk_bf16_f32 v226, v46, v47
	v_cvt_pk_bf16_f32 v227, v48, v49
	v_lshlrev_b32_e32 v176, 16, v228
	v_and_b32_e32 v177, 0xffff0000, v228
	v_lshlrev_b32_e32 v178, 16, v229
	v_and_b32_e32 v179, 0xffff0000, v229
	v_lshlrev_b32_e32 v180, 16, v230
	v_and_b32_e32 v181, 0xffff0000, v230
	v_lshlrev_b32_e32 v244, 16, v231
	v_and_b32_e32 v245, 0xffff0000, v231
	v_max_f32_e32 v176, s100, v176
	v_max_f32_e32 v177, s100, v177
	v_max_f32_e32 v178, s100, v178
	v_max_f32_e32 v179, s100, v179
	v_max_f32_e32 v180, s100, v180
	v_max_f32_e32 v181, s100, v181
	v_max_f32_e32 v244, s100, v244
	v_max_f32_e32 v245, s100, v245
	v_pk_mul_f32 v[34:35], v[34:35], v[176:177]
	v_pk_mul_f32 v[36:37], v[36:37], v[178:179]
	v_pk_mul_f32 v[26:27], v[26:27], v[180:181]
	v_pk_mul_f32 v[28:29], v[28:29], v[244:245]
	v_cvt_pk_bf16_f32 v228, v34, v35
	v_cvt_pk_bf16_f32 v229, v36, v37
	v_cvt_pk_bf16_f32 v230, v26, v27
	v_cvt_pk_bf16_f32 v231, v28, v29
	global_store_dwordx4 v[140:141], v[224:227], off offset:-4096
	global_store_dwordx4 v[140:141], v[228:231], off offset:-3840
	s_waitcnt vmcnt(12)
	v_lshlrev_b32_e32 v148, 16, v184
	v_and_b32_e32 v149, 0xffff0000, v184
	v_lshlrev_b32_e32 v150, 16, v185
	v_and_b32_e32 v151, 0xffff0000, v185
	v_lshlrev_b32_e32 v152, 16, v186
	v_and_b32_e32 v153, 0xffff0000, v186
	v_lshlrev_b32_e32 v168, 16, v187
	v_and_b32_e32 v169, 0xffff0000, v187
	v_max_f32_e32 v148, s100, v148
	v_max_f32_e32 v149, s100, v149
	v_max_f32_e32 v150, s100, v150
	v_max_f32_e32 v151, s100, v151
	v_max_f32_e32 v152, s100, v152
	v_max_f32_e32 v153, s100, v153
	v_max_f32_e32 v168, s100, v168
	v_max_f32_e32 v169, s100, v169
	v_pk_mul_f32 v[38:39], v[38:39], v[148:149]
	v_pk_mul_f32 v[40:41], v[40:41], v[150:151]
	v_pk_mul_f32 v[30:31], v[30:31], v[152:153]
	v_pk_mul_f32 v[32:33], v[32:33], v[168:169]
	v_cvt_pk_bf16_f32 v184, v38, v39
	v_cvt_pk_bf16_f32 v185, v40, v41
	v_cvt_pk_bf16_f32 v186, v30, v31
	v_cvt_pk_bf16_f32 v187, v32, v33
	v_lshlrev_b32_e32 v176, 16, v188
	v_and_b32_e32 v177, 0xffff0000, v188
	v_lshlrev_b32_e32 v178, 16, v189
	v_and_b32_e32 v179, 0xffff0000, v189
	v_lshlrev_b32_e32 v180, 16, v190
	v_and_b32_e32 v181, 0xffff0000, v190
	v_lshlrev_b32_e32 v244, 16, v191
	v_and_b32_e32 v245, 0xffff0000, v191
	v_max_f32_e32 v176, s100, v176
	v_max_f32_e32 v177, s100, v177
	v_max_f32_e32 v178, s100, v178
	v_max_f32_e32 v179, s100, v179
	v_max_f32_e32 v180, s100, v180
	v_max_f32_e32 v181, s100, v181
	v_max_f32_e32 v244, s100, v244
	v_max_f32_e32 v245, s100, v245
	v_pk_mul_f32 v[18:19], v[18:19], v[176:177]
	v_pk_mul_f32 v[20:21], v[20:21], v[178:179]
	v_pk_mul_f32 v[10:11], v[10:11], v[180:181]
	v_pk_mul_f32 v[12:13], v[12:13], v[244:245]
	v_cvt_pk_bf16_f32 v188, v18, v19
	v_cvt_pk_bf16_f32 v189, v20, v21
	v_cvt_pk_bf16_f32 v190, v10, v11
	v_cvt_pk_bf16_f32 v191, v12, v13
	global_store_dwordx4 v[142:143], v[184:187], off offset:-4096
	global_store_dwordx4 v[142:143], v[188:191], off offset:-3840
	s_waitcnt vmcnt(10)
	v_lshlrev_b32_e32 v148, 16, v192
	v_and_b32_e32 v149, 0xffff0000, v192
	v_lshlrev_b32_e32 v150, 16, v193
	v_and_b32_e32 v151, 0xffff0000, v193
	v_lshlrev_b32_e32 v152, 16, v194
	v_and_b32_e32 v153, 0xffff0000, v194
	v_lshlrev_b32_e32 v168, 16, v195
	v_and_b32_e32 v169, 0xffff0000, v195
	v_max_f32_e32 v148, s100, v148
	v_max_f32_e32 v149, s100, v149
	v_max_f32_e32 v150, s100, v150
	v_max_f32_e32 v151, s100, v151
	v_max_f32_e32 v152, s100, v152
	v_max_f32_e32 v153, s100, v153
	v_max_f32_e32 v168, s100, v168
	v_max_f32_e32 v169, s100, v169
	v_pk_mul_f32 v[22:23], v[22:23], v[148:149]
	v_pk_mul_f32 v[24:25], v[24:25], v[150:151]
	v_pk_mul_f32 v[14:15], v[14:15], v[152:153]
	v_pk_mul_f32 v[16:17], v[16:17], v[168:169]
	v_cvt_pk_bf16_f32 v192, v22, v23
	v_cvt_pk_bf16_f32 v193, v24, v25
	v_cvt_pk_bf16_f32 v194, v14, v15
	v_cvt_pk_bf16_f32 v195, v16, v17
	v_lshlrev_b32_e32 v176, 16, v196
	v_and_b32_e32 v177, 0xffff0000, v196
	v_lshlrev_b32_e32 v178, 16, v197
	v_and_b32_e32 v179, 0xffff0000, v197
	v_lshlrev_b32_e32 v180, 16, v198
	v_and_b32_e32 v181, 0xffff0000, v198
	v_lshlrev_b32_e32 v244, 16, v199
	v_and_b32_e32 v245, 0xffff0000, v199
	v_max_f32_e32 v176, s100, v176
	v_max_f32_e32 v177, s100, v177
	v_max_f32_e32 v178, s100, v178
	v_max_f32_e32 v179, s100, v179
	v_max_f32_e32 v180, s100, v180
	v_max_f32_e32 v181, s100, v181
	v_max_f32_e32 v244, s100, v244
	v_max_f32_e32 v245, s100, v245
	v_pk_mul_f32 v[6:7], v[6:7], v[176:177]
	v_pk_mul_f32 v[8:9], v[8:9], v[178:179]
	v_pk_mul_f32 v[2:3], v[2:3], v[180:181]
	v_pk_mul_f32 v[4:5], v[4:5], v[244:245]
	v_cvt_pk_bf16_f32 v196, v6, v7
	v_cvt_pk_bf16_f32 v197, v8, v9
	v_cvt_pk_bf16_f32 v198, v2, v3
	v_cvt_pk_bf16_f32 v199, v4, v5
	global_store_dwordx4 v[144:145], v[192:195], off offset:-4096
	global_store_dwordx4 v[144:145], v[196:199], off offset:-3840
.Lup6_tail:
	s_and_b64 vcc, exec, s[4:5]
	s_mov_b64 s[4:5], -1
	s_cbranch_vccnz .LBB0_1253
	s_andn2_b64 vcc, exec, s[10:11]
	s_cbranch_vccnz .LBB0_1252
	s_barrier
	s_branch .LBB0_1252

; __global__ void __launch_bounds__(512, 2) fwd_kernel(Params P) {
	.amdhsa_kernel _Z10fwd_kernel6Params
		.amdhsa_group_segment_fixed_size 0
		.amdhsa_private_segment_fixed_size 0
		.amdhsa_kernarg_size 480
		.amdhsa_user_sgpr_count 2
		.amdhsa_user_sgpr_dispatch_ptr 0
		.amdhsa_user_sgpr_queue_ptr 0
		.amdhsa_user_sgpr_kernarg_segment_ptr 1
		.amdhsa_user_sgpr_dispatch_id 0
		.amdhsa_user_sgpr_kernarg_preload_length 0
		.amdhsa_user_sgpr_kernarg_preload_offset 0
		.amdhsa_user_sgpr_private_segment_size 0
		.amdhsa_uses_dynamic_stack 0
		.amdhsa_enable_private_segment 0
		.amdhsa_system_sgpr_workgroup_id_x 1
		.amdhsa_system_sgpr_workgroup_id_y 0
		.amdhsa_system_sgpr_workgroup_id_z 0
		.amdhsa_system_sgpr_workgroup_info 0
		.amdhsa_system_vgpr_workitem_id 2
		.amdhsa_next_free_vgpr 248
		.amdhsa_next_free_sgpr 102
		.amdhsa_accum_offset 248
		.amdhsa_reserve_vcc 1
		.amdhsa_float_round_mode_32 0
		.amdhsa_float_round_mode_16_64 0
		.amdhsa_float_denorm_mode_32 3
		.amdhsa_float_denorm_mode_16_64 3
		.amdhsa_dx10_clamp 1
		.amdhsa_ieee_mode 1
		.amdhsa_fp16_overflow 0
		.amdhsa_tg_split 0
		.amdhsa_exception_fp_ieee_invalid_op 0
		.amdhsa_exception_fp_denorm_src 0
		.amdhsa_exception_fp_ieee_div_zero 0
		.amdhsa_exception_fp_ieee_overflow 0
		.amdhsa_exception_fp_ieee_underflow 0
		.amdhsa_exception_fp_ieee_inexact 0
		.amdhsa_exception_int_div_zero 0
	.end_amdhsa_kernel

; __global__ void __launch_bounds__(512, 2) fwd_kernel(Params P) {
amdhsa.kernels:
  - .agpr_count:     0
    .args:
      - .offset:         0
        .size:           224
        .value_kind:     by_value
      - .offset:         224
        .size:           4
        .value_kind:     hidden_block_count_x
      - .offset:         228
        .size:           4
        .value_kind:     hidden_block_count_y
      - .offset:         232
        .size:           4
        .value_kind:     hidden_block_count_z
      - .offset:         236
        .size:           2
        .value_kind:     hidden_group_size_x
      - .offset:         238
        .size:           2
        .value_kind:     hidden_group_size_y
      - .offset:         240
        .size:           2
        .value_kind:     hidden_group_size_z
      - .offset:         242
        .size:           2
        .value_kind:     hidden_remainder_x
      - .offset:         244
        .size:           2
        .value_kind:     hidden_remainder_y
      - .offset:         246
        .size:           2
        .value_kind:     hidden_remainder_z
      - .offset:         264
        .size:           8
        .value_kind:     hidden_global_offset_x
      - .offset:         272
        .size:           8
        .value_kind:     hidden_global_offset_y
      - .offset:         280
        .size:           8
        .value_kind:     hidden_global_offset_z
      - .offset:         288
        .size:           2
        .value_kind:     hidden_grid_dims
      - .offset:         312
        .size:           8
        .value_kind:     hidden_multigrid_sync_arg
      - .offset:         344
        .size:           4
        .value_kind:     hidden_dynamic_lds_size
    .group_segment_fixed_size: 0
    .kernarg_segment_align: 8
    .kernarg_segment_size: 480
    .language:       OpenCL C
    .language_version:
      - 2
      - 0
    .max_flat_workgroup_size: 512
    .name:           _Z10fwd_kernel6Params
    .private_segment_fixed_size: 0
    .sgpr_count:     108
    .sgpr_spill_count: 18
    .symbol:         _Z10fwd_kernel6Params.kd
    .uniform_work_group_size: 1
    .uses_dynamic_stack: false
    .vgpr_count:     248
    .vgpr_spill_count: 0
    .wavefront_size: 64
